# tile-setup zero seed: v_mov v0,0 + v_mov v1,v0 folded into one v_mov_b64 at 24 GEMM tile setups
# baseline (speedup 1.0000x reference)
;     ...
;         const bool has_next = S.next(ui + 1, nxt);
;         const char* nA = has_next ? (const char*)g.A + (size_t)nxt.pm * tA : cA; const char* nB = has_next ? (const char*)g.Bt + (size_t)nxt.pn * tB : cB;
;     ...
; #pragma unroll
;         for (int a = 0; a < 2; ++a)
; #pragma unroll
;             for (int b = 0; b < 2; ++b)
; #pragma unroll
;                 for (int m = 0; m < 4; ++m)
; #pragma unroll
;                     for (int n = 0; n < 2; ++n) acc[a][b][m][n] = (f32x4){0.f, 0.f, 0.f, 0.f};
;         cur = nxt; cA = nA; cB = nB; ++ui;
.LBB0_124:
	s_ashr_i32 s23, s22, 31
	v_cmp_lt_i64_e32 vcc, s[24:25], v[140:141]
	s_lshl_b64 s[24:25], s[22:23], 19
	s_add_u32 s24, s10, s24
	s_addc_u32 s25, s11, s25
	s_and_b64 s[26:27], vcc, exec
	s_cselect_b32 s7, s25, s35
	s_cselect_b32 s23, s24, s34
	s_ashr_i32 s21, s20, 31
	s_lshl_b64 s[26:27], s[20:21], 19
	s_add_u32 s26, s12, s26
	s_addc_u32 s27, s13, s27
	s_and_b64 s[36:37], vcc, exec
	s_cselect_b32 s21, s27, s31
	s_cselect_b32 s33, s26, s30
	s_add_u32 s42, s30, 0x100
	s_addc_u32 s43, s31, 0
	s_add_u32 s30, s34, 0x40080
	v_mov_b64_e32 v[0:1], 0
	s_addc_u32 s31, s35, 0
	s_mov_b32 s44, -2
	v_mov_b64_e32 v[2:3], 0
	v_mov_b64_e32 v[4:5], 0
	v_mov_b64_e32 v[6:7], 0
	v_mov_b64_e32 v[8:9], 0
	v_mov_b64_e32 v[10:11], 0
	v_mov_b64_e32 v[12:13], 0
	v_mov_b64_e32 v[14:15], 0
	v_mov_b64_e32 v[16:17], 0
	v_mov_b64_e32 v[18:19], 0
	v_mov_b64_e32 v[20:21], 0
	v_mov_b64_e32 v[22:23], 0
	v_mov_b64_e32 v[24:25], 0
	v_mov_b64_e32 v[26:27], 0
	v_mov_b64_e32 v[28:29], 0
	v_mov_b64_e32 v[30:31], 0
	v_mov_b64_e32 v[32:33], 0
	v_mov_b64_e32 v[34:35], 0
	v_mov_b64_e32 v[36:37], 0
	v_mov_b64_e32 v[38:39], 0
	v_mov_b64_e32 v[40:41], 0
	v_mov_b64_e32 v[42:43], 0
	v_mov_b64_e32 v[44:45], 0
	v_mov_b64_e32 v[46:47], 0
	v_mov_b64_e32 v[48:49], 0
	v_mov_b64_e32 v[50:51], 0
	v_mov_b64_e32 v[52:53], 0
	v_mov_b64_e32 v[54:55], 0
	v_mov_b64_e32 v[56:57], 0
	v_mov_b64_e32 v[58:59], 0
	v_mov_b64_e32 v[60:61], 0
	v_mov_b64_e32 v[62:63], 0
	v_mov_b64_e32 v[64:65], 0
	v_mov_b64_e32 v[66:67], 0
	v_mov_b64_e32 v[68:69], 0
	v_mov_b64_e32 v[70:71], 0
	v_mov_b64_e32 v[72:73], 0
	v_mov_b64_e32 v[74:75], 0
	v_mov_b64_e32 v[76:77], 0
	v_mov_b64_e32 v[78:79], 0
	v_mov_b64_e32 v[80:81], 0
	v_mov_b64_e32 v[82:83], 0
	v_mov_b64_e32 v[84:85], 0
	v_mov_b64_e32 v[86:87], 0
	v_mov_b64_e32 v[88:89], 0
	v_mov_b64_e32 v[90:91], 0
	v_mov_b64_e32 v[92:93], 0
	v_mov_b64_e32 v[94:95], 0
	v_mov_b64_e32 v[96:97], 0
	v_mov_b64_e32 v[98:99], 0
	v_mov_b64_e32 v[100:101], 0
	v_mov_b64_e32 v[102:103], 0
	v_mov_b64_e32 v[104:105], 0
	v_mov_b64_e32 v[106:107], 0
	v_mov_b64_e32 v[108:109], 0
	v_mov_b64_e32 v[110:111], 0
	v_mov_b64_e32 v[112:113], 0
	v_mov_b64_e32 v[114:115], 0
	v_mov_b64_e32 v[116:117], 0
	v_mov_b64_e32 v[118:119], 0
	v_mov_b64_e32 v[120:121], 0
	v_mov_b64_e32 v[122:123], 0
	v_mov_b64_e32 v[124:125], 0
	v_mov_b64_e32 v[126:127], 0

;     ...
;         const bool has_next = S.next(ui + 1, nxt);
;         const char* nA = has_next ? (const char*)g.A + (size_t)nxt.pm * tA : cA; const char* nB = has_next ? (const char*)g.Bt + (size_t)nxt.pn * tB : cB;
;     ...
; #pragma unroll
;         for (int a = 0; a < 2; ++a)
; #pragma unroll
;             for (int b = 0; b < 2; ++b)
; #pragma unroll
;                 for (int m = 0; m < 4; ++m)
; #pragma unroll
;                     for (int n = 0; n < 2; ++n) acc[a][b][m][n] = (f32x4){0.f, 0.f, 0.f, 0.f};
;         cur = nxt; cA = nA; cB = nB; ++ui;
.LBB0_331:
	s_ashr_i32 s29, s28, 31
	v_cmp_lt_i64_e32 vcc, s[30:31], v[138:139]
	s_lshl_b64 s[30:31], s[28:29], 17
	s_lshr_b32 s98, s26, 2
	s_lshl_b32 s98, s98, 8
	s_add_u32 s30, s30, s98
	s_add_u32 s30, s10, s30
	s_addc_u32 s31, s11, s31
	s_and_b64 s[34:35], vcc, exec
	s_cselect_b32 s7, s31, s41
	s_cselect_b32 s29, s30, s40
	s_ashr_i32 s27, s26, 31
	s_lshl_b64 s[34:35], s[26:27], 17
	s_add_u32 s34, s34, s98
	s_add_u32 s34, s12, s34
	s_addc_u32 s35, s13, s35
	s_and_b64 s[42:43], vcc, exec
	v_mov_b64_e32 v[0:1], 0
	s_cselect_b32 s27, s35, s39
	s_cselect_b32 s42, s34, s38
	s_mov_b64 s[60:61], 0
	s_mov_b64 s[56:57], 0
	s_mov_b64 s[58:59], -1
	v_mov_b64_e32 v[2:3], 0
	v_mov_b64_e32 v[4:5], 0
	v_mov_b64_e32 v[6:7], 0
	v_mov_b64_e32 v[8:9], 0
	v_mov_b64_e32 v[10:11], 0
	v_mov_b64_e32 v[12:13], 0
	v_mov_b64_e32 v[14:15], 0
	v_mov_b64_e32 v[16:17], 0
	v_mov_b64_e32 v[18:19], 0
	v_mov_b64_e32 v[20:21], 0
	v_mov_b64_e32 v[22:23], 0
	v_mov_b64_e32 v[24:25], 0
	v_mov_b64_e32 v[26:27], 0
	v_mov_b64_e32 v[28:29], 0
	v_mov_b64_e32 v[30:31], 0
	v_mov_b64_e32 v[32:33], 0
	v_mov_b64_e32 v[34:35], 0
	v_mov_b64_e32 v[36:37], 0
	v_mov_b64_e32 v[38:39], 0
	v_mov_b64_e32 v[40:41], 0
	v_mov_b64_e32 v[42:43], 0
	v_mov_b64_e32 v[44:45], 0
	v_mov_b64_e32 v[46:47], 0
	v_mov_b64_e32 v[48:49], 0
	v_mov_b64_e32 v[50:51], 0
	v_mov_b64_e32 v[52:53], 0
	v_mov_b64_e32 v[54:55], 0
	v_mov_b64_e32 v[56:57], 0
	v_mov_b64_e32 v[58:59], 0
	v_mov_b64_e32 v[60:61], 0
	v_mov_b64_e32 v[62:63], 0
	v_mov_b64_e32 v[64:65], 0
	v_mov_b64_e32 v[66:67], 0
	v_mov_b64_e32 v[68:69], 0
	v_mov_b64_e32 v[70:71], 0
	v_mov_b64_e32 v[72:73], 0
	v_mov_b64_e32 v[74:75], 0
	v_mov_b64_e32 v[76:77], 0
	v_mov_b64_e32 v[78:79], 0
	v_mov_b64_e32 v[80:81], 0
	v_mov_b64_e32 v[82:83], 0
	v_mov_b64_e32 v[84:85], 0
	v_mov_b64_e32 v[86:87], 0
	v_mov_b64_e32 v[88:89], 0
	v_mov_b64_e32 v[90:91], 0
	v_mov_b64_e32 v[92:93], 0
	v_mov_b64_e32 v[94:95], 0
	v_mov_b64_e32 v[96:97], 0
	v_mov_b64_e32 v[98:99], 0
	v_mov_b64_e32 v[100:101], 0
	v_mov_b64_e32 v[102:103], 0
	v_mov_b64_e32 v[104:105], 0
	v_mov_b64_e32 v[106:107], 0
	v_mov_b64_e32 v[108:109], 0
	v_mov_b64_e32 v[110:111], 0
	v_mov_b64_e32 v[112:113], 0
	v_mov_b64_e32 v[114:115], 0
	v_mov_b64_e32 v[116:117], 0
	v_mov_b64_e32 v[118:119], 0
	v_mov_b64_e32 v[120:121], 0
	v_mov_b64_e32 v[122:123], 0
	v_mov_b64_e32 v[124:125], 0
	v_mov_b64_e32 v[126:127], 0

;     ...
;         const bool has_next = S.next(ui + 1, nxt);
;         const char* nA = has_next ? (const char*)g.A + (size_t)nxt.pm * tA : cA; const char* nB = has_next ? (const char*)g.Bt + (size_t)nxt.pn * tB : cB;
;     ...
; #pragma unroll
;         for (int a = 0; a < 2; ++a)
; #pragma unroll
;             for (int b = 0; b < 2; ++b)
; #pragma unroll
;                 for (int m = 0; m < 4; ++m)
; #pragma unroll
;                     for (int n = 0; n < 2; ++n) acc[a][b][m][n] = (f32x4){0.f, 0.f, 0.f, 0.f};
;         cur = nxt; cA = nA; cB = nB; ++ui;
.LBB0_343:
	s_ashr_i32 s23, s22, 31
	v_cmp_lt_i64_e32 vcc, s[24:25], v[158:159]
	s_lshl_b64 s[24:25], s[22:23], 18
	s_lshl_b32 s98, s20, 9
	s_add_u32 s24, s24, s98
	s_add_u32 s24, s10, s24
	s_addc_u32 s25, s11, s25
	s_and_b64 s[26:27], vcc, exec
	s_cselect_b32 s7, s25, s35
	s_cselect_b32 s23, s24, s34
	s_ashr_i32 s21, s20, 31
	s_lshl_b64 s[26:27], s[20:21], 18
	s_add_u32 s26, s26, s98
	s_add_u32 s26, s12, s26
	s_addc_u32 s27, s13, s27
	s_and_b64 s[36:37], vcc, exec
	s_cselect_b32 s21, s27, s31
	s_cselect_b32 s33, s26, s30
	s_add_u32 s42, s30, 0x100
	s_addc_u32 s43, s31, 0
	s_add_u32 s30, s34, 0x20080
	v_mov_b64_e32 v[0:1], 0
	s_addc_u32 s31, s35, 0
	s_mov_b32 s44, -2
	v_mov_b64_e32 v[2:3], 0
	v_mov_b64_e32 v[4:5], 0
	v_mov_b64_e32 v[6:7], 0
	v_mov_b64_e32 v[8:9], 0
	v_mov_b64_e32 v[10:11], 0
	v_mov_b64_e32 v[12:13], 0
	v_mov_b64_e32 v[14:15], 0
	v_mov_b64_e32 v[16:17], 0
	v_mov_b64_e32 v[18:19], 0
	v_mov_b64_e32 v[20:21], 0
	v_mov_b64_e32 v[22:23], 0
	v_mov_b64_e32 v[24:25], 0
	v_mov_b64_e32 v[26:27], 0
	v_mov_b64_e32 v[28:29], 0
	v_mov_b64_e32 v[30:31], 0
	v_mov_b64_e32 v[32:33], 0
	v_mov_b64_e32 v[34:35], 0
	v_mov_b64_e32 v[36:37], 0
	v_mov_b64_e32 v[38:39], 0
	v_mov_b64_e32 v[40:41], 0
	v_mov_b64_e32 v[42:43], 0
	v_mov_b64_e32 v[44:45], 0
	v_mov_b64_e32 v[46:47], 0
	v_mov_b64_e32 v[48:49], 0
	v_mov_b64_e32 v[50:51], 0
	v_mov_b64_e32 v[52:53], 0
	v_mov_b64_e32 v[54:55], 0
	v_mov_b64_e32 v[56:57], 0
	v_mov_b64_e32 v[58:59], 0
	v_mov_b64_e32 v[60:61], 0
	v_mov_b64_e32 v[62:63], 0
	v_mov_b64_e32 v[64:65], 0
	v_mov_b64_e32 v[66:67], 0
	v_mov_b64_e32 v[68:69], 0
	v_mov_b64_e32 v[70:71], 0
	v_mov_b64_e32 v[72:73], 0
	v_mov_b64_e32 v[74:75], 0
	v_mov_b64_e32 v[76:77], 0
	v_mov_b64_e32 v[78:79], 0
	v_mov_b64_e32 v[80:81], 0
	v_mov_b64_e32 v[82:83], 0
	v_mov_b64_e32 v[84:85], 0
	v_mov_b64_e32 v[86:87], 0
	v_mov_b64_e32 v[88:89], 0
	v_mov_b64_e32 v[90:91], 0
	v_mov_b64_e32 v[92:93], 0
	v_mov_b64_e32 v[94:95], 0
	v_mov_b64_e32 v[96:97], 0
	v_mov_b64_e32 v[98:99], 0
	v_mov_b64_e32 v[100:101], 0
	v_mov_b64_e32 v[102:103], 0
	v_mov_b64_e32 v[104:105], 0
	v_mov_b64_e32 v[106:107], 0
	v_mov_b64_e32 v[108:109], 0
	v_mov_b64_e32 v[110:111], 0
	v_mov_b64_e32 v[112:113], 0
	v_mov_b64_e32 v[114:115], 0
	v_mov_b64_e32 v[116:117], 0
	v_mov_b64_e32 v[118:119], 0
	v_mov_b64_e32 v[120:121], 0
	v_mov_b64_e32 v[122:123], 0
	v_mov_b64_e32 v[124:125], 0
	v_mov_b64_e32 v[126:127], 0

;     ...
;         const bool has_next = S.next(ui + 1, nxt);
;         const char* nA = has_next ? (const char*)g.A + (size_t)nxt.pm * tA : cA; const char* nB = has_next ? (const char*)g.Bt + (size_t)nxt.pn * tB : cB;
;     ...
; #pragma unroll
;         for (int a = 0; a < 2; ++a)
; #pragma unroll
;             for (int b = 0; b < 2; ++b)
; #pragma unroll
;                 for (int m = 0; m < 4; ++m)
; #pragma unroll
;                     for (int n = 0; n < 2; ++n) acc[a][b][m][n] = (f32x4){0.f, 0.f, 0.f, 0.f};
;         cur = nxt; cA = nA; cB = nB; ++ui;
.LBB0_626:
	s_ashr_i32 s29, s28, 31
	s_lshl_b64 s[8:9], s[28:29], 18
	s_add_u32 s34, s22, s8
	s_addc_u32 s35, s23, s9
	s_and_b64 s[8:9], s[12:13], exec
	s_cselect_b32 s8, s35, s17
	s_cselect_b32 s9, s34, s16
	s_add_u32 s29, s16, 0x100
	v_mov_b64_e32 v[0:1], 0
	s_addc_u32 s33, s17, 0
	s_mov_b32 s42, -2
	v_mov_b64_e32 v[2:3], 0
	v_mov_b64_e32 v[4:5], 0
	v_mov_b64_e32 v[6:7], 0
	v_mov_b64_e32 v[8:9], 0
	v_mov_b64_e32 v[10:11], 0
	v_mov_b64_e32 v[12:13], 0
	v_mov_b64_e32 v[14:15], 0
	v_mov_b64_e32 v[16:17], 0
	v_mov_b64_e32 v[18:19], 0
	v_mov_b64_e32 v[20:21], 0
	v_mov_b64_e32 v[22:23], 0
	v_mov_b64_e32 v[24:25], 0
	v_mov_b64_e32 v[26:27], 0
	v_mov_b64_e32 v[28:29], 0
	v_mov_b64_e32 v[30:31], 0
	v_mov_b64_e32 v[32:33], 0
	v_mov_b64_e32 v[34:35], 0
	v_mov_b64_e32 v[36:37], 0
	v_mov_b64_e32 v[38:39], 0
	v_mov_b64_e32 v[40:41], 0
	v_mov_b64_e32 v[42:43], 0
	v_mov_b64_e32 v[44:45], 0
	v_mov_b64_e32 v[46:47], 0
	v_mov_b64_e32 v[48:49], 0
	v_mov_b64_e32 v[50:51], 0
	v_mov_b64_e32 v[52:53], 0
	v_mov_b64_e32 v[54:55], 0
	v_mov_b64_e32 v[56:57], 0
	v_mov_b64_e32 v[58:59], 0
	v_mov_b64_e32 v[60:61], 0
	v_mov_b64_e32 v[62:63], 0
	v_mov_b64_e32 v[64:65], 0
	v_mov_b64_e32 v[66:67], 0
	v_mov_b64_e32 v[68:69], 0
	v_mov_b64_e32 v[70:71], 0
	v_mov_b64_e32 v[72:73], 0
	v_mov_b64_e32 v[74:75], 0
	v_mov_b64_e32 v[76:77], 0
	v_mov_b64_e32 v[78:79], 0
	v_mov_b64_e32 v[80:81], 0
	v_mov_b64_e32 v[82:83], 0
	v_mov_b64_e32 v[84:85], 0
	v_mov_b64_e32 v[86:87], 0
	v_mov_b64_e32 v[88:89], 0
	v_mov_b64_e32 v[90:91], 0
	v_mov_b64_e32 v[92:93], 0
	v_mov_b64_e32 v[94:95], 0
	v_mov_b64_e32 v[96:97], 0
	v_mov_b64_e32 v[98:99], 0
	v_mov_b64_e32 v[100:101], 0
	v_mov_b64_e32 v[102:103], 0
	v_mov_b64_e32 v[104:105], 0
	v_mov_b64_e32 v[106:107], 0
	v_mov_b64_e32 v[108:109], 0
	v_mov_b64_e32 v[110:111], 0
	v_mov_b64_e32 v[112:113], 0
	v_mov_b64_e32 v[114:115], 0
	v_mov_b64_e32 v[116:117], 0
	v_mov_b64_e32 v[118:119], 0
	v_mov_b64_e32 v[120:121], 0
	v_mov_b64_e32 v[122:123], 0
	v_mov_b64_e32 v[124:125], 0
	v_mov_b64_e32 v[126:127], 0

;     ...
;         const bool has_next = S.next(ui + 1, nxt);
;         const char* nA = has_next ? (const char*)g.A + (size_t)nxt.pm * tA : cA; const char* nB = has_next ? (const char*)g.Bt + (size_t)nxt.pn * tB : cB;
;     ...
; #pragma unroll
;         for (int a = 0; a < 2; ++a)
; #pragma unroll
;             for (int b = 0; b < 2; ++b)
; #pragma unroll
;                 for (int m = 0; m < 4; ++m)
; #pragma unroll
;                     for (int n = 0; n < 2; ++n) acc[a][b][m][n] = (f32x4){0.f, 0.f, 0.f, 0.f};
;         cur = nxt; cA = nA; cB = nB; ++ui;
.LBB0_699:
	s_ashr_i32 s41, s40, 31
	s_lshl_b64 s[8:9], s[40:41], 18
	s_add_u32 s58, s64, s8
	v_cmp_lt_i64_e32 vcc, s[18:19], v[140:141]
	s_addc_u32 s59, s65, s9
	s_and_b64 s[8:9], vcc, exec
	s_cselect_b32 s7, s59, s15
	s_cselect_b32 s8, s58, s14
	s_ashr_i32 s61, s60, 31
	s_lshl_b64 s[18:19], s[60:61], 18
	s_add_u32 s56, s22, s18
	s_addc_u32 s57, s23, s19
	s_and_b64 s[18:19], vcc, exec
	s_cselect_b32 s9, s57, s17
	s_cselect_b32 s20, s56, s16
	s_add_u32 s21, s16, 0x100
	s_addc_u32 s33, s17, 0
	s_add_u32 s14, s14, 0x20080
	v_mov_b64_e32 v[0:1], 0
	s_addc_u32 s15, s15, 0
	s_mov_b32 s41, -2
	v_mov_b64_e32 v[2:3], 0
	v_mov_b64_e32 v[4:5], 0
	v_mov_b64_e32 v[6:7], 0
	v_mov_b64_e32 v[8:9], 0
	v_mov_b64_e32 v[10:11], 0
	v_mov_b64_e32 v[12:13], 0
	v_mov_b64_e32 v[14:15], 0
	v_mov_b64_e32 v[16:17], 0
	v_mov_b64_e32 v[18:19], 0
	v_mov_b64_e32 v[20:21], 0
	v_mov_b64_e32 v[22:23], 0
	v_mov_b64_e32 v[24:25], 0
	v_mov_b64_e32 v[26:27], 0
	v_mov_b64_e32 v[28:29], 0
	v_mov_b64_e32 v[30:31], 0
	v_mov_b64_e32 v[32:33], 0
	v_mov_b64_e32 v[34:35], 0
	v_mov_b64_e32 v[36:37], 0
	v_mov_b64_e32 v[38:39], 0
	v_mov_b64_e32 v[40:41], 0
	v_mov_b64_e32 v[42:43], 0
	v_mov_b64_e32 v[44:45], 0
	v_mov_b64_e32 v[46:47], 0
	v_mov_b64_e32 v[48:49], 0
	v_mov_b64_e32 v[50:51], 0
	v_mov_b64_e32 v[52:53], 0
	v_mov_b64_e32 v[54:55], 0
	v_mov_b64_e32 v[56:57], 0
	v_mov_b64_e32 v[58:59], 0
	v_mov_b64_e32 v[60:61], 0
	v_mov_b64_e32 v[62:63], 0
	v_mov_b64_e32 v[64:65], 0
	v_mov_b64_e32 v[66:67], 0
	v_mov_b64_e32 v[68:69], 0
	v_mov_b64_e32 v[70:71], 0
	v_mov_b64_e32 v[72:73], 0
	v_mov_b64_e32 v[74:75], 0
	v_mov_b64_e32 v[76:77], 0
	v_mov_b64_e32 v[78:79], 0
	v_mov_b64_e32 v[80:81], 0
	v_mov_b64_e32 v[82:83], 0
	v_mov_b64_e32 v[84:85], 0
	v_mov_b64_e32 v[86:87], 0
	v_mov_b64_e32 v[88:89], 0
	v_mov_b64_e32 v[90:91], 0
	v_mov_b64_e32 v[92:93], 0
	v_mov_b64_e32 v[94:95], 0
	v_mov_b64_e32 v[96:97], 0
	v_mov_b64_e32 v[98:99], 0
	v_mov_b64_e32 v[100:101], 0
	v_mov_b64_e32 v[102:103], 0
	v_mov_b64_e32 v[104:105], 0
	v_mov_b64_e32 v[106:107], 0
	v_mov_b64_e32 v[108:109], 0
	v_mov_b64_e32 v[110:111], 0
	v_mov_b64_e32 v[112:113], 0
	v_mov_b64_e32 v[114:115], 0
	v_mov_b64_e32 v[116:117], 0
	v_mov_b64_e32 v[118:119], 0
	v_mov_b64_e32 v[120:121], 0
	v_mov_b64_e32 v[122:123], 0
	v_mov_b64_e32 v[124:125], 0
	v_mov_b64_e32 v[126:127], 0

;     ...
;         const bool has_next = S.next(ui + 1, nxt);
;         const char* nA = has_next ? (const char*)g.A + (size_t)nxt.pm * tA : cA; const char* nB = has_next ? (const char*)g.Bt + (size_t)nxt.pn * tB : cB;
;     ...
; #pragma unroll
;         for (int a = 0; a < 2; ++a)
; #pragma unroll
;             for (int b = 0; b < 2; ++b)
; #pragma unroll
;                 for (int m = 0; m < 4; ++m)
; #pragma unroll
;                     for (int n = 0; n < 2; ++n) acc[a][b][m][n] = (f32x4){0.f, 0.f, 0.f, 0.f};
;         cur = nxt; cA = nA; cB = nB; ++ui;
.LBB0_722:
	s_ashr_i32 s39, s38, 31
	s_lshl_b64 s[8:9], s[38:39], 18
	s_add_u32 s56, s64, s8
	v_cmp_lt_i64_e64 s[16:17], s[16:17], 16
	s_addc_u32 s57, s65, s9
	s_and_b64 s[8:9], s[16:17], exec
	s_cselect_b32 s7, s57, s13
	s_cselect_b32 s8, s56, s12
	s_ashr_i32 s59, s58, 31
	s_lshl_b64 s[18:19], s[58:59], 18
	s_add_u32 s54, s24, s18
	s_addc_u32 s55, s25, s19
	s_and_b64 s[16:17], s[16:17], exec
	s_cselect_b32 s9, s55, s15
	s_cselect_b32 s18, s54, s14
	s_add_u32 s19, s14, 0x100
	s_addc_u32 s33, s15, 0
	s_add_u32 s12, s12, 0x20080
	v_mov_b64_e32 v[0:1], 0
	s_addc_u32 s13, s13, 0
	s_mov_b32 s39, -2
	v_mov_b64_e32 v[2:3], 0
	v_mov_b64_e32 v[4:5], 0
	v_mov_b64_e32 v[6:7], 0
	v_mov_b64_e32 v[8:9], 0
	v_mov_b64_e32 v[10:11], 0
	v_mov_b64_e32 v[12:13], 0
	v_mov_b64_e32 v[14:15], 0
	v_mov_b64_e32 v[16:17], 0
	v_mov_b64_e32 v[18:19], 0
	v_mov_b64_e32 v[20:21], 0
	v_mov_b64_e32 v[22:23], 0
	v_mov_b64_e32 v[24:25], 0
	v_mov_b64_e32 v[26:27], 0
	v_mov_b64_e32 v[28:29], 0
	v_mov_b64_e32 v[30:31], 0
	v_mov_b64_e32 v[32:33], 0
	v_mov_b64_e32 v[34:35], 0
	v_mov_b64_e32 v[36:37], 0
	v_mov_b64_e32 v[38:39], 0
	v_mov_b64_e32 v[40:41], 0
	v_mov_b64_e32 v[42:43], 0
	v_mov_b64_e32 v[44:45], 0
	v_mov_b64_e32 v[46:47], 0
	v_mov_b64_e32 v[48:49], 0
	v_mov_b64_e32 v[50:51], 0
	v_mov_b64_e32 v[52:53], 0
	v_mov_b64_e32 v[54:55], 0
	v_mov_b64_e32 v[56:57], 0
	v_mov_b64_e32 v[58:59], 0
	v_mov_b64_e32 v[60:61], 0
	v_mov_b64_e32 v[62:63], 0
	v_mov_b64_e32 v[64:65], 0
	v_mov_b64_e32 v[66:67], 0
	v_mov_b64_e32 v[68:69], 0
	v_mov_b64_e32 v[70:71], 0
	v_mov_b64_e32 v[72:73], 0
	v_mov_b64_e32 v[74:75], 0
	v_mov_b64_e32 v[76:77], 0
	v_mov_b64_e32 v[78:79], 0
	v_mov_b64_e32 v[80:81], 0
	v_mov_b64_e32 v[82:83], 0
	v_mov_b64_e32 v[84:85], 0
	v_mov_b64_e32 v[86:87], 0
	v_mov_b64_e32 v[88:89], 0
	v_mov_b64_e32 v[90:91], 0
	v_mov_b64_e32 v[92:93], 0
	v_mov_b64_e32 v[94:95], 0
	v_mov_b64_e32 v[96:97], 0
	v_mov_b64_e32 v[98:99], 0
	v_mov_b64_e32 v[100:101], 0
	v_mov_b64_e32 v[102:103], 0
	v_mov_b64_e32 v[104:105], 0
	v_mov_b64_e32 v[106:107], 0
	v_mov_b64_e32 v[108:109], 0
	v_mov_b64_e32 v[110:111], 0
	v_mov_b64_e32 v[112:113], 0
	v_mov_b64_e32 v[114:115], 0
	v_mov_b64_e32 v[116:117], 0
	v_mov_b64_e32 v[118:119], 0
	v_mov_b64_e32 v[120:121], 0
	v_mov_b64_e32 v[122:123], 0
	v_mov_b64_e32 v[124:125], 0
	v_mov_b64_e32 v[126:127], 0

;     ...
;         const bool has_next = S.next(ui + 1, nxt);
;         const char* nA = has_next ? (const char*)g.A + (size_t)nxt.pm * tA : cA; const char* nB = has_next ? (const char*)g.Bt + (size_t)nxt.pn * tB : cB;
;     ...
; #pragma unroll
;         for (int a = 0; a < 2; ++a)
; #pragma unroll
;             for (int b = 0; b < 2; ++b)
; #pragma unroll
;                 for (int m = 0; m < 4; ++m)
; #pragma unroll
;                     for (int n = 0; n < 2; ++n) acc[a][b][m][n] = (f32x4){0.f, 0.f, 0.f, 0.f};
;         cur = nxt; cA = nA; cB = nB; ++ui;
.LBB0_763:
	s_ashr_i32 s35, s34, 31
	s_lshl_b64 s[6:7], s[34:35], 19
	s_add_u32 s54, s20, s6
	s_addc_u32 s55, s21, s7
	s_and_b64 s[6:7], s[16:17], exec
	s_cselect_b32 s6, s55, s61
	s_cselect_b32 s7, s54, s60
	s_add_u32 s8, s58, 0x110000
	v_mov_b64_e32 v[0:1], 0
	s_addc_u32 s9, s59, 0
	s_mov_b32 s33, 0
	s_waitcnt lgkmcnt(0)
	v_mov_b64_e32 v[2:3], 0
	v_mov_b64_e32 v[4:5], 0
	v_mov_b64_e32 v[6:7], 0
	v_mov_b64_e32 v[8:9], 0
	v_mov_b64_e32 v[10:11], 0
	v_mov_b64_e32 v[12:13], 0
	v_mov_b64_e32 v[14:15], 0
	v_mov_b64_e32 v[16:17], 0
	v_mov_b64_e32 v[18:19], 0
	v_mov_b64_e32 v[20:21], 0
	v_mov_b64_e32 v[22:23], 0
	v_mov_b64_e32 v[24:25], 0
	v_mov_b64_e32 v[26:27], 0
	v_mov_b64_e32 v[28:29], 0
	v_mov_b64_e32 v[30:31], 0
	v_mov_b64_e32 v[32:33], 0
	v_mov_b64_e32 v[34:35], 0
	v_mov_b64_e32 v[36:37], 0
	v_mov_b64_e32 v[38:39], 0
	v_mov_b64_e32 v[40:41], 0
	v_mov_b64_e32 v[42:43], 0
	v_mov_b64_e32 v[44:45], 0
	v_mov_b64_e32 v[46:47], 0
	v_mov_b64_e32 v[48:49], 0
	v_mov_b64_e32 v[50:51], 0
	v_mov_b64_e32 v[52:53], 0
	v_mov_b64_e32 v[54:55], 0
	v_mov_b64_e32 v[56:57], 0
	v_mov_b64_e32 v[58:59], 0
	v_mov_b64_e32 v[60:61], 0
	v_mov_b64_e32 v[62:63], 0
	v_mov_b64_e32 v[64:65], 0
	v_mov_b64_e32 v[66:67], 0
	v_mov_b64_e32 v[68:69], 0
	v_mov_b64_e32 v[70:71], 0
	v_mov_b64_e32 v[72:73], 0
	v_mov_b64_e32 v[74:75], 0
	v_mov_b64_e32 v[76:77], 0
	v_mov_b64_e32 v[78:79], 0
	v_mov_b64_e32 v[80:81], 0
	v_mov_b64_e32 v[82:83], 0
	v_mov_b64_e32 v[84:85], 0
	v_mov_b64_e32 v[86:87], 0
	v_mov_b64_e32 v[88:89], 0
	v_mov_b64_e32 v[90:91], 0
	v_mov_b64_e32 v[92:93], 0
	v_mov_b64_e32 v[94:95], 0
	v_mov_b64_e32 v[96:97], 0
	v_mov_b64_e32 v[98:99], 0
	v_mov_b64_e32 v[100:101], 0
	v_mov_b64_e32 v[102:103], 0
	v_mov_b64_e32 v[104:105], 0
	v_mov_b64_e32 v[106:107], 0
	v_mov_b64_e32 v[108:109], 0
	v_mov_b64_e32 v[110:111], 0
	v_mov_b64_e32 v[112:113], 0
	v_mov_b64_e32 v[114:115], 0
	v_mov_b64_e32 v[116:117], 0
	v_mov_b64_e32 v[118:119], 0
	v_mov_b64_e32 v[120:121], 0
	v_mov_b64_e32 v[122:123], 0
	v_mov_b64_e32 v[124:125], 0
	v_mov_b64_e32 v[126:127], 0
	s_branch .LBB0_767

;     ...
;         const bool has_next = S.next(ui + 1, nxt);
;         const char* nA = has_next ? (const char*)g.A + (size_t)nxt.pm * tA : cA; const char* nB = has_next ? (const char*)g.Bt + (size_t)nxt.pn * tB : cB;
;     ...
; #pragma unroll
;         for (int a = 0; a < 2; ++a)
; #pragma unroll
;             for (int b = 0; b < 2; ++b)
; #pragma unroll
;                 for (int m = 0; m < 4; ++m)
; #pragma unroll
;                     for (int n = 0; n < 2; ++n) acc[a][b][m][n] = (f32x4){0.f, 0.f, 0.f, 0.f};
;         cur = nxt; cA = nA; cB = nB; ++ui;
.LBB0_836:
	s_ashr_i32 s59, s58, 31
	s_lshl_b64 s[64:65], s[58:59], 19
	s_add_u32 s64, s96, s64
	s_addc_u32 s65, s97, s65
	s_and_b64 s[66:67], s[60:61], exec
	v_mov_b64_e32 v[0:1], 0
	s_cselect_b32 s43, s65, s41
	s_cselect_b32 s59, s64, s40
	s_mov_b32 s78, 0
	s_mov_b64 s[70:71], -1
	s_mov_b64 s[66:67], 0
	v_mov_b64_e32 v[2:3], 0
	v_mov_b64_e32 v[4:5], 0
	v_mov_b64_e32 v[6:7], 0
	v_mov_b64_e32 v[8:9], 0
	v_mov_b64_e32 v[10:11], 0
	v_mov_b64_e32 v[12:13], 0
	v_mov_b64_e32 v[14:15], 0
	v_mov_b64_e32 v[16:17], 0
	v_mov_b64_e32 v[18:19], 0
	v_mov_b64_e32 v[20:21], 0
	v_mov_b64_e32 v[22:23], 0
	v_mov_b64_e32 v[24:25], 0
	v_mov_b64_e32 v[26:27], 0
	v_mov_b64_e32 v[28:29], 0
	v_mov_b64_e32 v[30:31], 0
	v_mov_b64_e32 v[32:33], 0
	v_mov_b64_e32 v[34:35], 0
	v_mov_b64_e32 v[36:37], 0
	v_mov_b64_e32 v[38:39], 0
	v_mov_b64_e32 v[40:41], 0
	v_mov_b64_e32 v[42:43], 0
	v_mov_b64_e32 v[44:45], 0
	v_mov_b64_e32 v[46:47], 0
	v_mov_b64_e32 v[48:49], 0
	v_mov_b64_e32 v[50:51], 0
	v_mov_b64_e32 v[52:53], 0
	v_mov_b64_e32 v[54:55], 0
	v_mov_b64_e32 v[56:57], 0
	v_mov_b64_e32 v[58:59], 0
	v_mov_b64_e32 v[60:61], 0
	v_mov_b64_e32 v[62:63], 0
	v_mov_b64_e32 v[64:65], 0
	v_mov_b64_e32 v[66:67], 0
	v_mov_b64_e32 v[68:69], 0
	v_mov_b64_e32 v[70:71], 0
	v_mov_b64_e32 v[72:73], 0
	v_mov_b64_e32 v[74:75], 0
	v_mov_b64_e32 v[76:77], 0
	v_mov_b64_e32 v[78:79], 0
	v_mov_b64_e32 v[80:81], 0
	v_mov_b64_e32 v[82:83], 0
	v_mov_b64_e32 v[84:85], 0
	v_mov_b64_e32 v[86:87], 0
	v_mov_b64_e32 v[88:89], 0
	v_mov_b64_e32 v[90:91], 0
	v_mov_b64_e32 v[92:93], 0
	v_mov_b64_e32 v[94:95], 0
	v_mov_b64_e32 v[96:97], 0
	v_mov_b64_e32 v[98:99], 0
	v_mov_b64_e32 v[100:101], 0
	v_mov_b64_e32 v[102:103], 0
	v_mov_b64_e32 v[104:105], 0
	v_mov_b64_e32 v[106:107], 0
	v_mov_b64_e32 v[108:109], 0
	v_mov_b64_e32 v[110:111], 0
	v_mov_b64_e32 v[112:113], 0
	v_mov_b64_e32 v[114:115], 0
	v_mov_b64_e32 v[116:117], 0
	v_mov_b64_e32 v[118:119], 0
	v_mov_b64_e32 v[120:121], 0
	v_mov_b64_e32 v[122:123], 0
	v_mov_b64_e32 v[124:125], 0
	v_mov_b64_e32 v[126:127], 0
	s_branch .LBB0_840

;     ...
;         const bool has_next = S.next(ui + 1, nxt);
;         const char* nA = has_next ? (const char*)g.A + (size_t)nxt.pm * tA : cA; const char* nB = has_next ? (const char*)g.Bt + (size_t)nxt.pn * tB : cB;
;     ...
; #pragma unroll
;         for (int a = 0; a < 2; ++a)
; #pragma unroll
;             for (int b = 0; b < 2; ++b)
; #pragma unroll
;                 for (int m = 0; m < 4; ++m)
; #pragma unroll
;                     for (int n = 0; n < 2; ++n) acc[a][b][m][n] = (f32x4){0.f, 0.f, 0.f, 0.f};
;         cur = nxt; cA = nA; cB = nB; ++ui;
.LBB0_957:
	s_ashr_i32 s29, s28, 31
	s_lshl_b64 s[8:9], s[28:29], 19
	s_add_u32 s36, s14, s8
	v_cmp_lt_i64_e32 vcc, s[34:35], v[140:141]
	s_addc_u32 s37, s15, s9
	s_and_b64 s[8:9], vcc, exec
	s_cselect_b32 s7, s37, s41
	s_cselect_b32 s8, s36, s40
	s_ashr_i32 s39, s38, 31
	s_lshl_b64 s[34:35], s[38:39], 19
	s_add_u32 s34, s24, s34
	s_addc_u32 s35, s25, s35
	s_and_b64 s[42:43], vcc, exec
	s_cselect_b32 s9, s35, s55
	s_cselect_b32 s29, s34, s54
	s_add_u32 s33, s54, 0x100
	s_addc_u32 s39, s55, 0
	s_add_u32 s40, s40, 0x40080
	v_mov_b64_e32 v[0:1], 0
	s_addc_u32 s41, s41, 0
	s_mov_b32 s42, -2
	v_mov_b64_e32 v[2:3], 0
	v_mov_b64_e32 v[4:5], 0
	v_mov_b64_e32 v[6:7], 0
	v_mov_b64_e32 v[8:9], 0
	v_mov_b64_e32 v[10:11], 0
	v_mov_b64_e32 v[12:13], 0
	v_mov_b64_e32 v[14:15], 0
	v_mov_b64_e32 v[16:17], 0
	v_mov_b64_e32 v[18:19], 0
	v_mov_b64_e32 v[20:21], 0
	v_mov_b64_e32 v[22:23], 0
	v_mov_b64_e32 v[24:25], 0
	v_mov_b64_e32 v[26:27], 0
	v_mov_b64_e32 v[28:29], 0
	v_mov_b64_e32 v[30:31], 0
	v_mov_b64_e32 v[32:33], 0
	v_mov_b64_e32 v[34:35], 0
	v_mov_b64_e32 v[36:37], 0
	v_mov_b64_e32 v[38:39], 0
	v_mov_b64_e32 v[40:41], 0
	v_mov_b64_e32 v[42:43], 0
	v_mov_b64_e32 v[44:45], 0
	v_mov_b64_e32 v[46:47], 0
	v_mov_b64_e32 v[48:49], 0
	v_mov_b64_e32 v[50:51], 0
	v_mov_b64_e32 v[52:53], 0
	v_mov_b64_e32 v[54:55], 0
	v_mov_b64_e32 v[56:57], 0
	v_mov_b64_e32 v[58:59], 0
	v_mov_b64_e32 v[60:61], 0
	v_mov_b64_e32 v[62:63], 0
	v_mov_b64_e32 v[64:65], 0
	v_mov_b64_e32 v[66:67], 0
	v_mov_b64_e32 v[68:69], 0
	v_mov_b64_e32 v[70:71], 0
	v_mov_b64_e32 v[72:73], 0
	v_mov_b64_e32 v[74:75], 0
	v_mov_b64_e32 v[76:77], 0
	v_mov_b64_e32 v[78:79], 0
	v_mov_b64_e32 v[80:81], 0
	v_mov_b64_e32 v[82:83], 0
	v_mov_b64_e32 v[84:85], 0
	v_mov_b64_e32 v[86:87], 0
	v_mov_b64_e32 v[88:89], 0
	v_mov_b64_e32 v[90:91], 0
	v_mov_b64_e32 v[92:93], 0
	v_mov_b64_e32 v[94:95], 0
	v_mov_b64_e32 v[96:97], 0
	v_mov_b64_e32 v[98:99], 0
	v_mov_b64_e32 v[100:101], 0
	v_mov_b64_e32 v[102:103], 0
	v_mov_b64_e32 v[104:105], 0
	v_mov_b64_e32 v[106:107], 0
	v_mov_b64_e32 v[108:109], 0
	v_mov_b64_e32 v[110:111], 0
	v_mov_b64_e32 v[112:113], 0
	v_mov_b64_e32 v[114:115], 0
	v_mov_b64_e32 v[116:117], 0
	v_mov_b64_e32 v[118:119], 0
	v_mov_b64_e32 v[120:121], 0
	v_mov_b64_e32 v[122:123], 0
	v_mov_b64_e32 v[124:125], 0
	v_mov_b64_e32 v[126:127], 0

;     ...
;         const bool has_next = S.next(ui + 1, nxt);
;         const char* nA = has_next ? (const char*)g.A + (size_t)nxt.pm * tA : cA; const char* nB = has_next ? (const char*)g.Bt + (size_t)nxt.pn * tB : cB;
;     ...
; #pragma unroll
;         for (int a = 0; a < 2; ++a)
; #pragma unroll
;             for (int b = 0; b < 2; ++b)
; #pragma unroll
;                 for (int m = 0; m < 4; ++m)
; #pragma unroll
;                     for (int n = 0; n < 2; ++n) acc[a][b][m][n] = (f32x4){0.f, 0.f, 0.f, 0.f};
;         cur = nxt; cA = nA; cB = nB; ++ui;
.LBB0_980:
	s_ashr_i32 s25, s24, 31
	s_lshl_b64 s[8:9], s[24:25], 19
	s_add_u32 s30, s58, s8
	v_cmp_lt_i64_e64 s[54:55], s[28:29], 64
	s_addc_u32 s31, s59, s9
	s_and_b64 s[8:9], s[54:55], exec
	s_cselect_b32 s7, s31, s39
	s_cselect_b32 s8, s30, s38
	s_ashr_i32 s35, s34, 31
	s_lshl_b64 s[28:29], s[34:35], 19
	s_add_u32 s28, s16, s28
	s_addc_u32 s29, s17, s29
	s_and_b64 s[42:43], s[54:55], exec
	s_cselect_b32 s9, s29, s41
	s_cselect_b32 s25, s28, s40
	s_add_u32 s33, s40, 0x100
	s_addc_u32 s35, s41, 0
	s_add_u32 s38, s38, 0x40080
	v_mov_b64_e32 v[0:1], 0
	s_addc_u32 s39, s39, 0
	s_mov_b32 s42, -2
	v_mov_b64_e32 v[2:3], 0
	v_mov_b64_e32 v[4:5], 0
	v_mov_b64_e32 v[6:7], 0
	v_mov_b64_e32 v[8:9], 0
	v_mov_b64_e32 v[10:11], 0
	v_mov_b64_e32 v[12:13], 0
	v_mov_b64_e32 v[14:15], 0
	v_mov_b64_e32 v[16:17], 0
	v_mov_b64_e32 v[18:19], 0
	v_mov_b64_e32 v[20:21], 0
	v_mov_b64_e32 v[22:23], 0
	v_mov_b64_e32 v[24:25], 0
	v_mov_b64_e32 v[26:27], 0
	v_mov_b64_e32 v[28:29], 0
	v_mov_b64_e32 v[30:31], 0
	v_mov_b64_e32 v[32:33], 0
	v_mov_b64_e32 v[34:35], 0
	v_mov_b64_e32 v[36:37], 0
	v_mov_b64_e32 v[38:39], 0
	v_mov_b64_e32 v[40:41], 0
	v_mov_b64_e32 v[42:43], 0
	v_mov_b64_e32 v[44:45], 0
	v_mov_b64_e32 v[46:47], 0
	v_mov_b64_e32 v[48:49], 0
	v_mov_b64_e32 v[50:51], 0
	v_mov_b64_e32 v[52:53], 0
	v_mov_b64_e32 v[54:55], 0
	v_mov_b64_e32 v[56:57], 0
	v_mov_b64_e32 v[58:59], 0
	v_mov_b64_e32 v[60:61], 0
	v_mov_b64_e32 v[62:63], 0
	v_mov_b64_e32 v[64:65], 0
	v_mov_b64_e32 v[66:67], 0
	v_mov_b64_e32 v[68:69], 0
	v_mov_b64_e32 v[70:71], 0
	v_mov_b64_e32 v[72:73], 0
	v_mov_b64_e32 v[74:75], 0
	v_mov_b64_e32 v[76:77], 0
	v_mov_b64_e32 v[78:79], 0
	v_mov_b64_e32 v[80:81], 0
	v_mov_b64_e32 v[82:83], 0
	v_mov_b64_e32 v[84:85], 0
	v_mov_b64_e32 v[86:87], 0
	v_mov_b64_e32 v[88:89], 0
	v_mov_b64_e32 v[90:91], 0
	v_mov_b64_e32 v[92:93], 0
	v_mov_b64_e32 v[94:95], 0
	v_mov_b64_e32 v[96:97], 0
	v_mov_b64_e32 v[98:99], 0
	v_mov_b64_e32 v[100:101], 0
	v_mov_b64_e32 v[102:103], 0
	v_mov_b64_e32 v[104:105], 0
	v_mov_b64_e32 v[106:107], 0
	v_mov_b64_e32 v[108:109], 0
	v_mov_b64_e32 v[110:111], 0
	v_mov_b64_e32 v[112:113], 0
	v_mov_b64_e32 v[114:115], 0
	v_mov_b64_e32 v[116:117], 0
	v_mov_b64_e32 v[118:119], 0
	v_mov_b64_e32 v[120:121], 0
	v_mov_b64_e32 v[122:123], 0
	v_mov_b64_e32 v[124:125], 0
	v_mov_b64_e32 v[126:127], 0

;     ...
;         const bool has_next = S.next(ui + 1, nxt);
;         const char* nA = has_next ? (const char*)g.A + (size_t)nxt.pm * tA : cA; const char* nB = has_next ? (const char*)g.Bt + (size_t)nxt.pn * tB : cB;
;     ...
; #pragma unroll
;         for (int a = 0; a < 2; ++a)
; #pragma unroll
;             for (int b = 0; b < 2; ++b)
; #pragma unroll
;                 for (int m = 0; m < 4; ++m)
; #pragma unroll
;                     for (int n = 0; n < 2; ++n) acc[a][b][m][n] = (f32x4){0.f, 0.f, 0.f, 0.f};
;         cur = nxt; cA = nA; cB = nB; ++ui;
.LBB0_1019:
	s_ashr_i32 s39, s38, 31
	s_lshl_b64 s[6:7], s[38:39], 21
	s_add_u32 s40, s18, s6
	s_addc_u32 s41, s19, s7
	s_and_b64 s[6:7], s[16:17], exec
	s_cselect_b32 s6, s41, s61
	s_cselect_b32 s7, s40, s60
	s_ashr_i32 s37, s36, 31
	s_lshl_b64 s[8:9], s[36:37], 21
	s_add_u32 s54, s24, s8
	s_addc_u32 s55, s25, s9
	s_and_b64 s[8:9], s[16:17], exec
	s_cselect_b32 s8, s55, s63
	s_cselect_b32 s9, s54, s62
	s_add_u32 s33, s60, 0x100000
	s_addc_u32 s37, s61, 0
	s_lshl_b32 s42, s38, 6
	s_ashr_i32 s43, s42, 31
	s_lshl_b64 s[42:43], s[42:43], 2
	s_add_u32 s64, s73, s42
	v_mov_b64_e32 v[0:1], 0
	s_addc_u32 s65, s74, s43
	s_mov_b32 s39, 0
	s_waitcnt lgkmcnt(0)
	v_mov_b64_e32 v[2:3], 0
	v_mov_b64_e32 v[4:5], 0
	v_mov_b64_e32 v[6:7], 0
	v_mov_b64_e32 v[8:9], 0
	v_mov_b64_e32 v[10:11], 0
	v_mov_b64_e32 v[12:13], 0
	v_mov_b64_e32 v[14:15], 0
	v_mov_b64_e32 v[16:17], 0
	v_mov_b64_e32 v[18:19], 0
	v_mov_b64_e32 v[20:21], 0
	v_mov_b64_e32 v[22:23], 0
	v_mov_b64_e32 v[24:25], 0
	v_mov_b64_e32 v[26:27], 0
	v_mov_b64_e32 v[28:29], 0
	v_mov_b64_e32 v[30:31], 0
	v_mov_b64_e32 v[32:33], 0
	v_mov_b64_e32 v[34:35], 0
	v_mov_b64_e32 v[36:37], 0
	v_mov_b64_e32 v[38:39], 0
	v_mov_b64_e32 v[40:41], 0
	v_mov_b64_e32 v[42:43], 0
	v_mov_b64_e32 v[44:45], 0
	v_mov_b64_e32 v[46:47], 0
	v_mov_b64_e32 v[48:49], 0
	v_mov_b64_e32 v[50:51], 0
	v_mov_b64_e32 v[52:53], 0
	v_mov_b64_e32 v[54:55], 0
	v_mov_b64_e32 v[56:57], 0
	v_mov_b64_e32 v[58:59], 0
	v_mov_b64_e32 v[60:61], 0
	v_mov_b64_e32 v[62:63], 0
	v_mov_b64_e32 v[64:65], 0
	v_mov_b64_e32 v[66:67], 0
	v_mov_b64_e32 v[68:69], 0
	v_mov_b64_e32 v[70:71], 0
	v_mov_b64_e32 v[72:73], 0
	v_mov_b64_e32 v[74:75], 0
	v_mov_b64_e32 v[76:77], 0
	v_mov_b64_e32 v[78:79], 0
	v_mov_b64_e32 v[80:81], 0
	v_mov_b64_e32 v[82:83], 0
	v_mov_b64_e32 v[84:85], 0
	v_mov_b64_e32 v[86:87], 0
	v_mov_b64_e32 v[88:89], 0
	v_mov_b64_e32 v[90:91], 0
	v_mov_b64_e32 v[92:93], 0
	v_mov_b64_e32 v[94:95], 0
	v_mov_b64_e32 v[96:97], 0
	v_mov_b64_e32 v[98:99], 0
	v_mov_b64_e32 v[100:101], 0
	v_mov_b64_e32 v[102:103], 0
	v_mov_b64_e32 v[104:105], 0
	v_mov_b64_e32 v[106:107], 0
	v_mov_b64_e32 v[108:109], 0
	v_mov_b64_e32 v[110:111], 0
	v_mov_b64_e32 v[112:113], 0
	v_mov_b64_e32 v[114:115], 0
	v_mov_b64_e32 v[116:117], 0
	v_mov_b64_e32 v[118:119], 0
	v_mov_b64_e32 v[120:121], 0
	v_mov_b64_e32 v[122:123], 0
	v_mov_b64_e32 v[124:125], 0
	v_mov_b64_e32 v[126:127], 0
	s_branch .LBB0_1023

;     ...
;         const bool has_next = S.next(ui + 1, nxt);
;         const char* nA = has_next ? (const char*)g.A + (size_t)nxt.pm * tA : cA; const char* nB = has_next ? (const char*)g.Bt + (size_t)nxt.pn * tB : cB;
;     ...
; #pragma unroll
;         for (int a = 0; a < 2; ++a)
; #pragma unroll
;             for (int b = 0; b < 2; ++b)
; #pragma unroll
;                 for (int m = 0; m < 4; ++m)
; #pragma unroll
;                     for (int n = 0; n < 2; ++n) acc[a][b][m][n] = (f32x4){0.f, 0.f, 0.f, 0.f};
;         cur = nxt; cA = nA; cB = nB; ++ui;
.LBB0_1088:
	s_ashr_i32 s55, s54, 31
	s_lshl_b64 s[8:9], s[54:55], 21
	s_add_u32 s56, s87, s8
	s_addc_u32 s57, s88, s9
	s_and_b64 s[8:9], s[58:59], exec
	s_cselect_b32 s8, s57, s31
	s_cselect_b32 s9, s56, s30
	s_ashr_i32 s41, s40, 31
	s_lshl_b64 s[42:43], s[40:41], 21
	s_add_u32 s60, s89, s42
	s_addc_u32 s61, s90, s43
	s_and_b64 s[42:43], s[58:59], exec
	s_cselect_b32 s41, s61, s35
	s_cselect_b32 s42, s60, s34
	s_add_u32 s43, s30, 0x100000
	s_addc_u32 s45, s31, 0
	s_lshl_b32 s62, s54, 6
	s_ashr_i32 s63, s62, 31
	s_lshl_b64 s[62:63], s[62:63], 2
	s_add_u32 s62, s73, s62
	v_mov_b64_e32 v[0:1], 0
	s_addc_u32 s63, s74, s63
	s_mov_b32 s55, 0
	v_mov_b64_e32 v[2:3], 0
	v_mov_b64_e32 v[4:5], 0
	v_mov_b64_e32 v[6:7], 0
	v_mov_b64_e32 v[8:9], 0
	v_mov_b64_e32 v[10:11], 0
	v_mov_b64_e32 v[12:13], 0
	v_mov_b64_e32 v[14:15], 0
	v_mov_b64_e32 v[16:17], 0
	v_mov_b64_e32 v[18:19], 0
	v_mov_b64_e32 v[20:21], 0
	v_mov_b64_e32 v[22:23], 0
	v_mov_b64_e32 v[24:25], 0
	v_mov_b64_e32 v[26:27], 0
	v_mov_b64_e32 v[28:29], 0
	v_mov_b64_e32 v[30:31], 0
	v_mov_b64_e32 v[32:33], 0
	v_mov_b64_e32 v[34:35], 0
	v_mov_b64_e32 v[36:37], 0
	v_mov_b64_e32 v[38:39], 0
	v_mov_b64_e32 v[40:41], 0
	v_mov_b64_e32 v[42:43], 0
	v_mov_b64_e32 v[44:45], 0
	v_mov_b64_e32 v[46:47], 0
	v_mov_b64_e32 v[48:49], 0
	v_mov_b64_e32 v[50:51], 0
	v_mov_b64_e32 v[52:53], 0
	v_mov_b64_e32 v[54:55], 0
	v_mov_b64_e32 v[56:57], 0
	v_mov_b64_e32 v[58:59], 0
	v_mov_b64_e32 v[60:61], 0
	v_mov_b64_e32 v[62:63], 0
	v_mov_b64_e32 v[64:65], 0
	v_mov_b64_e32 v[66:67], 0
	v_mov_b64_e32 v[68:69], 0
	v_mov_b64_e32 v[70:71], 0
	v_mov_b64_e32 v[72:73], 0
	v_mov_b64_e32 v[74:75], 0
	v_mov_b64_e32 v[76:77], 0
	v_mov_b64_e32 v[78:79], 0
	v_mov_b64_e32 v[80:81], 0
	v_mov_b64_e32 v[82:83], 0
	v_mov_b64_e32 v[84:85], 0
	v_mov_b64_e32 v[86:87], 0
	v_mov_b64_e32 v[88:89], 0
	v_mov_b64_e32 v[90:91], 0
	v_mov_b64_e32 v[92:93], 0
	v_mov_b64_e32 v[94:95], 0
	v_mov_b64_e32 v[96:97], 0
	v_mov_b64_e32 v[98:99], 0
	v_mov_b64_e32 v[100:101], 0
	v_mov_b64_e32 v[102:103], 0
	v_mov_b64_e32 v[104:105], 0
	v_mov_b64_e32 v[106:107], 0
	v_mov_b64_e32 v[108:109], 0
	v_mov_b64_e32 v[110:111], 0
	v_mov_b64_e32 v[112:113], 0
	v_mov_b64_e32 v[114:115], 0
	v_mov_b64_e32 v[116:117], 0
	v_mov_b64_e32 v[118:119], 0
	v_mov_b64_e32 v[120:121], 0
	v_mov_b64_e32 v[122:123], 0
	v_mov_b64_e32 v[124:125], 0
	v_mov_b64_e32 v[126:127], 0
	s_branch .LBB0_1092

;     ...
;         const bool has_next = S.next(ui + 1, nxt);
;         const char* nA = has_next ? (const char*)g.A + (size_t)nxt.pm * tA : cA; const char* nB = has_next ? (const char*)g.Bt + (size_t)nxt.pn * tB : cB;
;     ...
; #pragma unroll
;         for (int a = 0; a < 2; ++a)
; #pragma unroll
;             for (int b = 0; b < 2; ++b)
; #pragma unroll
;                 for (int m = 0; m < 4; ++m)
; #pragma unroll
;                     for (int n = 0; n < 2; ++n) acc[a][b][m][n] = (f32x4){0.f, 0.f, 0.f, 0.f};
;         cur = nxt; cA = nA; cB = nB; ++ui;
.LBB0_1287:
	s_ashr_i32 s25, s24, 31
	s_lshl_b64 s[8:9], s[24:25], 19
	v_cmp_lt_i64_e32 vcc, s[26:27], v[140:141]
	s_add_u32 s26, s12, s8
	s_addc_u32 s27, s13, s9
	s_and_b64 s[8:9], vcc, exec
	s_cselect_b32 s7, s27, s37
	s_cselect_b32 s8, s26, s36
	s_ashr_i32 s23, s22, 31
	s_lshl_b64 s[28:29], s[22:23], 19
	s_add_u32 s28, s14, s28
	s_addc_u32 s29, s15, s29
	s_and_b64 s[38:39], vcc, exec
	s_cselect_b32 s9, s29, s35
	s_cselect_b32 s23, s28, s34
	s_add_u32 s25, s34, 0x100
	s_addc_u32 s33, s35, 0
	s_add_u32 s34, s36, 0x40080
	v_mov_b64_e32 v[0:1], 0
	s_addc_u32 s35, s37, 0
	s_mov_b32 s42, -2
	v_mov_b64_e32 v[2:3], 0
	v_mov_b64_e32 v[4:5], 0
	v_mov_b64_e32 v[6:7], 0
	v_mov_b64_e32 v[8:9], 0
	v_mov_b64_e32 v[10:11], 0
	v_mov_b64_e32 v[12:13], 0
	v_mov_b64_e32 v[14:15], 0
	v_mov_b64_e32 v[16:17], 0
	v_mov_b64_e32 v[18:19], 0
	v_mov_b64_e32 v[20:21], 0
	v_mov_b64_e32 v[22:23], 0
	v_mov_b64_e32 v[24:25], 0
	v_mov_b64_e32 v[26:27], 0
	v_mov_b64_e32 v[28:29], 0
	v_mov_b64_e32 v[30:31], 0
	v_mov_b64_e32 v[32:33], 0
	v_mov_b64_e32 v[34:35], 0
	v_mov_b64_e32 v[36:37], 0
	v_mov_b64_e32 v[38:39], 0
	v_mov_b64_e32 v[40:41], 0
	v_mov_b64_e32 v[42:43], 0
	v_mov_b64_e32 v[44:45], 0
	v_mov_b64_e32 v[46:47], 0
	v_mov_b64_e32 v[48:49], 0
	v_mov_b64_e32 v[50:51], 0
	v_mov_b64_e32 v[52:53], 0
	v_mov_b64_e32 v[54:55], 0
	v_mov_b64_e32 v[56:57], 0
	v_mov_b64_e32 v[58:59], 0
	v_mov_b64_e32 v[60:61], 0
	v_mov_b64_e32 v[62:63], 0
	v_mov_b64_e32 v[64:65], 0
	v_mov_b64_e32 v[66:67], 0
	v_mov_b64_e32 v[68:69], 0
	v_mov_b64_e32 v[70:71], 0
	v_mov_b64_e32 v[72:73], 0
	v_mov_b64_e32 v[74:75], 0
	v_mov_b64_e32 v[76:77], 0
	v_mov_b64_e32 v[78:79], 0
	v_mov_b64_e32 v[80:81], 0
	v_mov_b64_e32 v[82:83], 0
	v_mov_b64_e32 v[84:85], 0
	v_mov_b64_e32 v[86:87], 0
	v_mov_b64_e32 v[88:89], 0
	v_mov_b64_e32 v[90:91], 0
	v_mov_b64_e32 v[92:93], 0
	v_mov_b64_e32 v[94:95], 0
	v_mov_b64_e32 v[96:97], 0
	v_mov_b64_e32 v[98:99], 0
	v_mov_b64_e32 v[100:101], 0
	v_mov_b64_e32 v[102:103], 0
	v_mov_b64_e32 v[104:105], 0
	v_mov_b64_e32 v[106:107], 0
	v_mov_b64_e32 v[108:109], 0
	v_mov_b64_e32 v[110:111], 0
	v_mov_b64_e32 v[112:113], 0
	v_mov_b64_e32 v[114:115], 0
	v_mov_b64_e32 v[116:117], 0
	v_mov_b64_e32 v[118:119], 0
	v_mov_b64_e32 v[120:121], 0
	v_mov_b64_e32 v[122:123], 0
	v_mov_b64_e32 v[124:125], 0
	v_mov_b64_e32 v[126:127], 0

;     ...
;         const bool has_next = S.next(ui + 1, nxt);
;         const char* nA = has_next ? (const char*)g.A + (size_t)nxt.pm * tA : cA; const char* nB = has_next ? (const char*)g.Bt + (size_t)nxt.pn * tB : cB;
;     ...
; #pragma unroll
;         for (int a = 0; a < 2; ++a)
; #pragma unroll
;             for (int b = 0; b < 2; ++b)
; #pragma unroll
;                 for (int m = 0; m < 4; ++m)
; #pragma unroll
;                     for (int n = 0; n < 2; ++n) acc[a][b][m][n] = (f32x4){0.f, 0.f, 0.f, 0.f};
;         cur = nxt; cA = nA; cB = nB; ++ui;
.LBB0_1472:
	s_ashr_i32 s31, s30, 31
	s_lshl_b64 s[8:9], s[30:31], 17
	s_lshr_b32 s98, s28, 2
	s_lshl_b32 s98, s98, 8
	s_add_u32 s8, s8, s98
	v_cmp_lt_i64_e32 vcc, s[34:35], v[138:139]
	s_add_u32 s34, s12, s8
	s_addc_u32 s35, s13, s9
	s_and_b64 s[8:9], vcc, exec
	s_cselect_b32 s7, s35, s43
	s_cselect_b32 s8, s34, s42
	s_ashr_i32 s29, s28, 31
	s_lshl_b64 s[36:37], s[28:29], 17
	s_add_u32 s36, s36, s98
	s_add_u32 s36, s14, s36
	s_addc_u32 s37, s15, s37
	s_and_b64 s[44:45], vcc, exec
	v_mov_b64_e32 v[0:1], 0
	s_cselect_b32 s9, s37, s41
	s_cselect_b32 s29, s36, s40
	s_mov_b64 s[58:59], 0
	s_mov_b64 s[54:55], 0
	s_mov_b64 s[56:57], -1
	v_mov_b64_e32 v[2:3], 0
	v_mov_b64_e32 v[4:5], 0
	v_mov_b64_e32 v[6:7], 0
	v_mov_b64_e32 v[8:9], 0
	v_mov_b64_e32 v[10:11], 0
	v_mov_b64_e32 v[12:13], 0
	v_mov_b64_e32 v[14:15], 0
	v_mov_b64_e32 v[16:17], 0
	v_mov_b64_e32 v[18:19], 0
	v_mov_b64_e32 v[20:21], 0
	v_mov_b64_e32 v[22:23], 0
	v_mov_b64_e32 v[24:25], 0
	v_mov_b64_e32 v[26:27], 0
	v_mov_b64_e32 v[28:29], 0
	v_mov_b64_e32 v[30:31], 0
	v_mov_b64_e32 v[32:33], 0
	v_mov_b64_e32 v[34:35], 0
	v_mov_b64_e32 v[36:37], 0
	v_mov_b64_e32 v[38:39], 0
	v_mov_b64_e32 v[40:41], 0
	v_mov_b64_e32 v[42:43], 0
	v_mov_b64_e32 v[44:45], 0
	v_mov_b64_e32 v[46:47], 0
	v_mov_b64_e32 v[48:49], 0
	v_mov_b64_e32 v[50:51], 0
	v_mov_b64_e32 v[52:53], 0
	v_mov_b64_e32 v[54:55], 0
	v_mov_b64_e32 v[56:57], 0
	v_mov_b64_e32 v[58:59], 0
	v_mov_b64_e32 v[60:61], 0
	v_mov_b64_e32 v[62:63], 0
	v_mov_b64_e32 v[64:65], 0
	v_mov_b64_e32 v[66:67], 0
	v_mov_b64_e32 v[68:69], 0
	v_mov_b64_e32 v[70:71], 0
	v_mov_b64_e32 v[72:73], 0
	v_mov_b64_e32 v[74:75], 0
	v_mov_b64_e32 v[76:77], 0
	v_mov_b64_e32 v[78:79], 0
	v_mov_b64_e32 v[80:81], 0
	v_mov_b64_e32 v[82:83], 0
	v_mov_b64_e32 v[84:85], 0
	v_mov_b64_e32 v[86:87], 0
	v_mov_b64_e32 v[88:89], 0
	v_mov_b64_e32 v[90:91], 0
	v_mov_b64_e32 v[92:93], 0
	v_mov_b64_e32 v[94:95], 0
	v_mov_b64_e32 v[96:97], 0
	v_mov_b64_e32 v[98:99], 0
	v_mov_b64_e32 v[100:101], 0
	v_mov_b64_e32 v[102:103], 0
	v_mov_b64_e32 v[104:105], 0
	v_mov_b64_e32 v[106:107], 0
	v_mov_b64_e32 v[108:109], 0
	v_mov_b64_e32 v[110:111], 0
	v_mov_b64_e32 v[112:113], 0
	v_mov_b64_e32 v[114:115], 0
	v_mov_b64_e32 v[116:117], 0
	v_mov_b64_e32 v[118:119], 0
	v_mov_b64_e32 v[120:121], 0
	v_mov_b64_e32 v[122:123], 0
	v_mov_b64_e32 v[124:125], 0
	v_mov_b64_e32 v[126:127], 0

;     ...
;         const bool has_next = S.next(ui + 1, nxt);
;         const char* nA = has_next ? (const char*)g.A + (size_t)nxt.pm * tA : cA; const char* nB = has_next ? (const char*)g.Bt + (size_t)nxt.pn * tB : cB;
;     ...
; #pragma unroll
;         for (int a = 0; a < 2; ++a)
; #pragma unroll
;             for (int b = 0; b < 2; ++b)
; #pragma unroll
;                 for (int m = 0; m < 4; ++m)
; #pragma unroll
;                     for (int n = 0; n < 2; ++n) acc[a][b][m][n] = (f32x4){0.f, 0.f, 0.f, 0.f};
;         cur = nxt; cA = nA; cB = nB; ++ui;
.LBB0_1484:
	s_ashr_i32 s25, s24, 31
	s_lshl_b64 s[8:9], s[24:25], 18
	s_lshl_b32 s98, s22, 9
	s_add_u32 s8, s8, s98
	v_cmp_lt_i64_e32 vcc, s[26:27], v[158:159]
	s_add_u32 s26, s12, s8
	s_addc_u32 s27, s13, s9
	s_and_b64 s[8:9], vcc, exec
	s_cselect_b32 s7, s27, s37
	s_cselect_b32 s8, s26, s36
	s_ashr_i32 s23, s22, 31
	s_lshl_b64 s[28:29], s[22:23], 18
	s_add_u32 s28, s28, s98
	s_add_u32 s28, s14, s28
	s_addc_u32 s29, s15, s29
	s_and_b64 s[38:39], vcc, exec
	s_cselect_b32 s9, s29, s35
	s_cselect_b32 s23, s28, s34
	s_add_u32 s25, s34, 0x100
	s_addc_u32 s33, s35, 0
	s_add_u32 s34, s36, 0x20080
	v_mov_b64_e32 v[0:1], 0
	s_addc_u32 s35, s37, 0
	s_mov_b32 s44, -2
	v_mov_b64_e32 v[2:3], 0
	v_mov_b64_e32 v[4:5], 0
	v_mov_b64_e32 v[6:7], 0
	v_mov_b64_e32 v[8:9], 0
	v_mov_b64_e32 v[10:11], 0
	v_mov_b64_e32 v[12:13], 0
	v_mov_b64_e32 v[14:15], 0
	v_mov_b64_e32 v[16:17], 0
	v_mov_b64_e32 v[18:19], 0
	v_mov_b64_e32 v[20:21], 0
	v_mov_b64_e32 v[22:23], 0
	v_mov_b64_e32 v[24:25], 0
	v_mov_b64_e32 v[26:27], 0
	v_mov_b64_e32 v[28:29], 0
	v_mov_b64_e32 v[30:31], 0
	v_mov_b64_e32 v[32:33], 0
	v_mov_b64_e32 v[34:35], 0
	v_mov_b64_e32 v[36:37], 0
	v_mov_b64_e32 v[38:39], 0
	v_mov_b64_e32 v[40:41], 0
	v_mov_b64_e32 v[42:43], 0
	v_mov_b64_e32 v[44:45], 0
	v_mov_b64_e32 v[46:47], 0
	v_mov_b64_e32 v[48:49], 0
	v_mov_b64_e32 v[50:51], 0
	v_mov_b64_e32 v[52:53], 0
	v_mov_b64_e32 v[54:55], 0
	v_mov_b64_e32 v[56:57], 0
	v_mov_b64_e32 v[58:59], 0
	v_mov_b64_e32 v[60:61], 0
	v_mov_b64_e32 v[62:63], 0
	v_mov_b64_e32 v[64:65], 0
	v_mov_b64_e32 v[66:67], 0
	v_mov_b64_e32 v[68:69], 0
	v_mov_b64_e32 v[70:71], 0
	v_mov_b64_e32 v[72:73], 0
	v_mov_b64_e32 v[74:75], 0
	v_mov_b64_e32 v[76:77], 0
	v_mov_b64_e32 v[78:79], 0
	v_mov_b64_e32 v[80:81], 0
	v_mov_b64_e32 v[82:83], 0
	v_mov_b64_e32 v[84:85], 0
	v_mov_b64_e32 v[86:87], 0
	v_mov_b64_e32 v[88:89], 0
	v_mov_b64_e32 v[90:91], 0
	v_mov_b64_e32 v[92:93], 0
	v_mov_b64_e32 v[94:95], 0
	v_mov_b64_e32 v[96:97], 0
	v_mov_b64_e32 v[98:99], 0
	v_mov_b64_e32 v[100:101], 0
	v_mov_b64_e32 v[102:103], 0
	v_mov_b64_e32 v[104:105], 0
	v_mov_b64_e32 v[106:107], 0
	v_mov_b64_e32 v[108:109], 0
	v_mov_b64_e32 v[110:111], 0
	v_mov_b64_e32 v[112:113], 0
	v_mov_b64_e32 v[114:115], 0
	v_mov_b64_e32 v[116:117], 0
	v_mov_b64_e32 v[118:119], 0
	v_mov_b64_e32 v[120:121], 0
	v_mov_b64_e32 v[122:123], 0
	v_mov_b64_e32 v[124:125], 0
	v_mov_b64_e32 v[126:127], 0

;     ...
;         const bool has_next = S.next(ui + 1, nxt);
;         const char* nA = has_next ? (const char*)g.A + (size_t)nxt.pm * tA : cA; const char* nB = has_next ? (const char*)g.Bt + (size_t)nxt.pn * tB : cB;
;     ...
; #pragma unroll
;         for (int a = 0; a < 2; ++a)
; #pragma unroll
;             for (int b = 0; b < 2; ++b)
; #pragma unroll
;                 for (int m = 0; m < 4; ++m)
; #pragma unroll
;                     for (int n = 0; n < 2; ++n) acc[a][b][m][n] = (f32x4){0.f, 0.f, 0.f, 0.f};
;         cur = nxt; cA = nA; cB = nB; ++ui;
.LBB0_1767:
	s_ashr_i32 s27, s26, 31
	s_lshl_b64 s[16:17], s[26:27], 18
	s_add_u32 s30, s20, s16
	s_addc_u32 s31, s21, s17
	s_and_b64 s[10:11], s[10:11], exec
	s_cselect_b32 s27, s31, s15
	s_cselect_b32 s33, s30, s14
	s_add_u32 s44, s14, 0x100
	v_mov_b64_e32 v[0:1], 0
	s_addc_u32 s45, s15, 0
	s_mov_b32 s60, -2
	v_mov_b64_e32 v[2:3], 0
	v_mov_b64_e32 v[4:5], 0
	v_mov_b64_e32 v[6:7], 0
	v_mov_b64_e32 v[8:9], 0
	v_mov_b64_e32 v[10:11], 0
	v_mov_b64_e32 v[12:13], 0
	v_mov_b64_e32 v[14:15], 0
	v_mov_b64_e32 v[16:17], 0
	v_mov_b64_e32 v[18:19], 0
	v_mov_b64_e32 v[20:21], 0
	v_mov_b64_e32 v[22:23], 0
	v_mov_b64_e32 v[24:25], 0
	v_mov_b64_e32 v[26:27], 0
	v_mov_b64_e32 v[28:29], 0
	v_mov_b64_e32 v[30:31], 0
	v_mov_b64_e32 v[32:33], 0
	v_mov_b64_e32 v[34:35], 0
	v_mov_b64_e32 v[36:37], 0
	v_mov_b64_e32 v[38:39], 0
	v_mov_b64_e32 v[40:41], 0
	v_mov_b64_e32 v[42:43], 0
	v_mov_b64_e32 v[44:45], 0
	v_mov_b64_e32 v[46:47], 0
	v_mov_b64_e32 v[48:49], 0
	v_mov_b64_e32 v[50:51], 0
	v_mov_b64_e32 v[52:53], 0
	v_mov_b64_e32 v[54:55], 0
	v_mov_b64_e32 v[56:57], 0
	v_mov_b64_e32 v[58:59], 0
	v_mov_b64_e32 v[60:61], 0
	v_mov_b64_e32 v[62:63], 0
	v_mov_b64_e32 v[64:65], 0
	v_mov_b64_e32 v[66:67], 0
	v_mov_b64_e32 v[68:69], 0
	v_mov_b64_e32 v[70:71], 0
	v_mov_b64_e32 v[72:73], 0
	v_mov_b64_e32 v[74:75], 0
	v_mov_b64_e32 v[76:77], 0
	v_mov_b64_e32 v[78:79], 0
	v_mov_b64_e32 v[80:81], 0
	v_mov_b64_e32 v[82:83], 0
	v_mov_b64_e32 v[84:85], 0
	v_mov_b64_e32 v[86:87], 0
	v_mov_b64_e32 v[88:89], 0
	v_mov_b64_e32 v[90:91], 0
	v_mov_b64_e32 v[92:93], 0
	v_mov_b64_e32 v[94:95], 0
	v_mov_b64_e32 v[96:97], 0
	v_mov_b64_e32 v[98:99], 0
	v_mov_b64_e32 v[100:101], 0
	v_mov_b64_e32 v[102:103], 0
	v_mov_b64_e32 v[104:105], 0
	v_mov_b64_e32 v[106:107], 0
	v_mov_b64_e32 v[108:109], 0
	v_mov_b64_e32 v[110:111], 0
	v_mov_b64_e32 v[112:113], 0
	v_mov_b64_e32 v[114:115], 0
	v_mov_b64_e32 v[116:117], 0
	v_mov_b64_e32 v[118:119], 0
	v_mov_b64_e32 v[120:121], 0
	v_mov_b64_e32 v[122:123], 0
	v_mov_b64_e32 v[124:125], 0
	v_mov_b64_e32 v[126:127], 0

;     ...
;         const bool has_next = S.next(ui + 1, nxt);
;         const char* nA = has_next ? (const char*)g.A + (size_t)nxt.pm * tA : cA; const char* nB = has_next ? (const char*)g.Bt + (size_t)nxt.pn * tB : cB;
;     ...
; #pragma unroll
;         for (int a = 0; a < 2; ++a)
; #pragma unroll
;             for (int b = 0; b < 2; ++b)
; #pragma unroll
;                 for (int m = 0; m < 4; ++m)
; #pragma unroll
;                     for (int n = 0; n < 2; ++n) acc[a][b][m][n] = (f32x4){0.f, 0.f, 0.f, 0.f};
;         cur = nxt; cA = nA; cB = nB; ++ui;
.LBB0_1840:
	s_ashr_i32 s39, s38, 31
	v_cmp_lt_i64_e32 vcc, s[16:17], v[140:141]
	s_lshl_b64 s[16:17], s[38:39], 18
	s_add_u32 s52, s58, s16
	s_addc_u32 s53, s59, s17
	s_and_b64 s[16:17], vcc, exec
	s_cselect_b32 s7, s53, s13
	s_cselect_b32 s18, s52, s12
	s_ashr_i32 s55, s54, 31
	s_lshl_b64 s[16:17], s[54:55], 18
	s_add_u32 s42, s34, s16
	s_addc_u32 s43, s35, s17
	s_and_b64 s[16:17], vcc, exec
	s_cselect_b32 s19, s43, s15
	s_cselect_b32 s33, s42, s14
	s_add_u32 s39, s14, 0x100
	s_addc_u32 s44, s15, 0
	s_add_u32 s12, s12, 0x20080
	v_mov_b64_e32 v[0:1], 0
	s_addc_u32 s13, s13, 0
	s_mov_b32 s45, -2
	v_mov_b64_e32 v[2:3], 0
	v_mov_b64_e32 v[4:5], 0
	v_mov_b64_e32 v[6:7], 0
	v_mov_b64_e32 v[8:9], 0
	v_mov_b64_e32 v[10:11], 0
	v_mov_b64_e32 v[12:13], 0
	v_mov_b64_e32 v[14:15], 0
	v_mov_b64_e32 v[16:17], 0
	v_mov_b64_e32 v[18:19], 0
	v_mov_b64_e32 v[20:21], 0
	v_mov_b64_e32 v[22:23], 0
	v_mov_b64_e32 v[24:25], 0
	v_mov_b64_e32 v[26:27], 0
	v_mov_b64_e32 v[28:29], 0
	v_mov_b64_e32 v[30:31], 0
	v_mov_b64_e32 v[32:33], 0
	v_mov_b64_e32 v[34:35], 0
	v_mov_b64_e32 v[36:37], 0
	v_mov_b64_e32 v[38:39], 0
	v_mov_b64_e32 v[40:41], 0
	v_mov_b64_e32 v[42:43], 0
	v_mov_b64_e32 v[44:45], 0
	v_mov_b64_e32 v[46:47], 0
	v_mov_b64_e32 v[48:49], 0
	v_mov_b64_e32 v[50:51], 0
	v_mov_b64_e32 v[52:53], 0
	v_mov_b64_e32 v[54:55], 0
	v_mov_b64_e32 v[56:57], 0
	v_mov_b64_e32 v[58:59], 0
	v_mov_b64_e32 v[60:61], 0
	v_mov_b64_e32 v[62:63], 0
	v_mov_b64_e32 v[64:65], 0
	v_mov_b64_e32 v[66:67], 0
	v_mov_b64_e32 v[68:69], 0
	v_mov_b64_e32 v[70:71], 0
	v_mov_b64_e32 v[72:73], 0
	v_mov_b64_e32 v[74:75], 0
	v_mov_b64_e32 v[76:77], 0
	v_mov_b64_e32 v[78:79], 0
	v_mov_b64_e32 v[80:81], 0
	v_mov_b64_e32 v[82:83], 0
	v_mov_b64_e32 v[84:85], 0
	v_mov_b64_e32 v[86:87], 0
	v_mov_b64_e32 v[88:89], 0
	v_mov_b64_e32 v[90:91], 0
	v_mov_b64_e32 v[92:93], 0
	v_mov_b64_e32 v[94:95], 0
	v_mov_b64_e32 v[96:97], 0
	v_mov_b64_e32 v[98:99], 0
	v_mov_b64_e32 v[100:101], 0
	v_mov_b64_e32 v[102:103], 0
	v_mov_b64_e32 v[104:105], 0
	v_mov_b64_e32 v[106:107], 0
	v_mov_b64_e32 v[108:109], 0
	v_mov_b64_e32 v[110:111], 0
	v_mov_b64_e32 v[112:113], 0
	v_mov_b64_e32 v[114:115], 0
	v_mov_b64_e32 v[116:117], 0
	v_mov_b64_e32 v[118:119], 0
	v_mov_b64_e32 v[120:121], 0
	v_mov_b64_e32 v[122:123], 0
	v_mov_b64_e32 v[124:125], 0
	v_mov_b64_e32 v[126:127], 0

;     ...
;         const bool has_next = S.next(ui + 1, nxt);
;         const char* nA = has_next ? (const char*)g.A + (size_t)nxt.pm * tA : cA; const char* nB = has_next ? (const char*)g.Bt + (size_t)nxt.pn * tB : cB;
;     ...
; #pragma unroll
;         for (int a = 0; a < 2; ++a)
; #pragma unroll
;             for (int b = 0; b < 2; ++b)
; #pragma unroll
;                 for (int m = 0; m < 4; ++m)
; #pragma unroll
;                     for (int n = 0; n < 2; ++n) acc[a][b][m][n] = (f32x4){0.f, 0.f, 0.f, 0.f};
;         cur = nxt; cA = nA; cB = nB; ++ui;
.LBB0_1863:
	s_ashr_i32 s37, s36, 31
	s_lshl_b64 s[16:17], s[36:37], 18
	s_add_u32 s42, s58, s16
	v_cmp_lt_i64_e64 s[14:15], s[14:15], 16
	s_addc_u32 s43, s59, s17
	s_and_b64 s[16:17], s[14:15], exec
	s_cselect_b32 s7, s43, s11
	s_cselect_b32 s16, s42, s10
	s_ashr_i32 s53, s52, 31
	s_lshl_b64 s[40:41], s[52:53], 18
	s_add_u32 s40, s18, s40
	s_addc_u32 s41, s19, s41
	s_and_b64 s[14:15], s[14:15], exec
	s_cselect_b32 s17, s41, s13
	s_cselect_b32 s33, s40, s12
	s_add_u32 s37, s12, 0x100
	s_addc_u32 s44, s13, 0
	s_add_u32 s10, s10, 0x20080
	v_mov_b64_e32 v[0:1], 0
	s_addc_u32 s11, s11, 0
	s_mov_b32 s45, -2
	v_mov_b64_e32 v[2:3], 0
	v_mov_b64_e32 v[4:5], 0
	v_mov_b64_e32 v[6:7], 0
	v_mov_b64_e32 v[8:9], 0
	v_mov_b64_e32 v[10:11], 0
	v_mov_b64_e32 v[12:13], 0
	v_mov_b64_e32 v[14:15], 0
	v_mov_b64_e32 v[16:17], 0
	v_mov_b64_e32 v[18:19], 0
	v_mov_b64_e32 v[20:21], 0
	v_mov_b64_e32 v[22:23], 0
	v_mov_b64_e32 v[24:25], 0
	v_mov_b64_e32 v[26:27], 0
	v_mov_b64_e32 v[28:29], 0
	v_mov_b64_e32 v[30:31], 0
	v_mov_b64_e32 v[32:33], 0
	v_mov_b64_e32 v[34:35], 0
	v_mov_b64_e32 v[36:37], 0
	v_mov_b64_e32 v[38:39], 0
	v_mov_b64_e32 v[40:41], 0
	v_mov_b64_e32 v[42:43], 0
	v_mov_b64_e32 v[44:45], 0
	v_mov_b64_e32 v[46:47], 0
	v_mov_b64_e32 v[48:49], 0
	v_mov_b64_e32 v[50:51], 0
	v_mov_b64_e32 v[52:53], 0
	v_mov_b64_e32 v[54:55], 0
	v_mov_b64_e32 v[56:57], 0
	v_mov_b64_e32 v[58:59], 0
	v_mov_b64_e32 v[60:61], 0
	v_mov_b64_e32 v[62:63], 0
	v_mov_b64_e32 v[64:65], 0
	v_mov_b64_e32 v[66:67], 0
	v_mov_b64_e32 v[68:69], 0
	v_mov_b64_e32 v[70:71], 0
	v_mov_b64_e32 v[72:73], 0
	v_mov_b64_e32 v[74:75], 0
	v_mov_b64_e32 v[76:77], 0
	v_mov_b64_e32 v[78:79], 0
	v_mov_b64_e32 v[80:81], 0
	v_mov_b64_e32 v[82:83], 0
	v_mov_b64_e32 v[84:85], 0
	v_mov_b64_e32 v[86:87], 0
	v_mov_b64_e32 v[88:89], 0
	v_mov_b64_e32 v[90:91], 0
	v_mov_b64_e32 v[92:93], 0
	v_mov_b64_e32 v[94:95], 0
	v_mov_b64_e32 v[96:97], 0
	v_mov_b64_e32 v[98:99], 0
	v_mov_b64_e32 v[100:101], 0
	v_mov_b64_e32 v[102:103], 0
	v_mov_b64_e32 v[104:105], 0
	v_mov_b64_e32 v[106:107], 0
	v_mov_b64_e32 v[108:109], 0
	v_mov_b64_e32 v[110:111], 0
	v_mov_b64_e32 v[112:113], 0
	v_mov_b64_e32 v[114:115], 0
	v_mov_b64_e32 v[116:117], 0
	v_mov_b64_e32 v[118:119], 0
	v_mov_b64_e32 v[120:121], 0
	v_mov_b64_e32 v[122:123], 0
	v_mov_b64_e32 v[124:125], 0
	v_mov_b64_e32 v[126:127], 0

;     ...
;         const bool has_next = S.next(ui + 1, nxt);
;         const char* nA = has_next ? (const char*)g.A + (size_t)nxt.pm * tA : cA; const char* nB = has_next ? (const char*)g.Bt + (size_t)nxt.pn * tB : cB;
;     ...
; #pragma unroll
;         for (int a = 0; a < 2; ++a)
; #pragma unroll
;             for (int b = 0; b < 2; ++b)
; #pragma unroll
;                 for (int m = 0; m < 4; ++m)
; #pragma unroll
;                     for (int n = 0; n < 2; ++n) acc[a][b][m][n] = (f32x4){0.f, 0.f, 0.f, 0.f};
;         cur = nxt; cA = nA; cB = nB; ++ui;
.LBB0_1904:
	s_ashr_i32 s29, s28, 31
	s_lshl_b64 s[6:7], s[28:29], 19
	s_add_u32 s38, s18, s6
	s_addc_u32 s39, s19, s7
	s_and_b64 s[6:7], s[14:15], exec
	s_cselect_b32 s6, s39, s53
	s_cselect_b32 s7, s38, s52
	s_add_u32 s29, s42, 0x110000
	v_mov_b64_e32 v[0:1], 0
	s_addc_u32 s33, s43, 0
	s_mov_b32 s41, 0
	s_waitcnt lgkmcnt(0)
	v_mov_b64_e32 v[2:3], 0
	v_mov_b64_e32 v[4:5], 0
	v_mov_b64_e32 v[6:7], 0
	v_mov_b64_e32 v[8:9], 0
	v_mov_b64_e32 v[10:11], 0
	v_mov_b64_e32 v[12:13], 0
	v_mov_b64_e32 v[14:15], 0
	v_mov_b64_e32 v[16:17], 0
	v_mov_b64_e32 v[18:19], 0
	v_mov_b64_e32 v[20:21], 0
	v_mov_b64_e32 v[22:23], 0
	v_mov_b64_e32 v[24:25], 0
	v_mov_b64_e32 v[26:27], 0
	v_mov_b64_e32 v[28:29], 0
	v_mov_b64_e32 v[30:31], 0
	v_mov_b64_e32 v[32:33], 0
	v_mov_b64_e32 v[34:35], 0
	v_mov_b64_e32 v[36:37], 0
	v_mov_b64_e32 v[38:39], 0
	v_mov_b64_e32 v[40:41], 0
	v_mov_b64_e32 v[42:43], 0
	v_mov_b64_e32 v[44:45], 0
	v_mov_b64_e32 v[46:47], 0
	v_mov_b64_e32 v[48:49], 0
	v_mov_b64_e32 v[50:51], 0
	v_mov_b64_e32 v[52:53], 0
	v_mov_b64_e32 v[54:55], 0
	v_mov_b64_e32 v[56:57], 0
	v_mov_b64_e32 v[58:59], 0
	v_mov_b64_e32 v[60:61], 0
	v_mov_b64_e32 v[62:63], 0
	v_mov_b64_e32 v[64:65], 0
	v_mov_b64_e32 v[66:67], 0
	v_mov_b64_e32 v[68:69], 0
	v_mov_b64_e32 v[70:71], 0
	v_mov_b64_e32 v[72:73], 0
	v_mov_b64_e32 v[74:75], 0
	v_mov_b64_e32 v[76:77], 0
	v_mov_b64_e32 v[78:79], 0
	v_mov_b64_e32 v[80:81], 0
	v_mov_b64_e32 v[82:83], 0
	v_mov_b64_e32 v[84:85], 0
	v_mov_b64_e32 v[86:87], 0
	v_mov_b64_e32 v[88:89], 0
	v_mov_b64_e32 v[90:91], 0
	v_mov_b64_e32 v[92:93], 0
	v_mov_b64_e32 v[94:95], 0
	v_mov_b64_e32 v[96:97], 0
	v_mov_b64_e32 v[98:99], 0
	v_mov_b64_e32 v[100:101], 0
	v_mov_b64_e32 v[102:103], 0
	v_mov_b64_e32 v[104:105], 0
	v_mov_b64_e32 v[106:107], 0
	v_mov_b64_e32 v[108:109], 0
	v_mov_b64_e32 v[110:111], 0
	v_mov_b64_e32 v[112:113], 0
	v_mov_b64_e32 v[114:115], 0
	v_mov_b64_e32 v[116:117], 0
	v_mov_b64_e32 v[118:119], 0
	v_mov_b64_e32 v[120:121], 0
	v_mov_b64_e32 v[122:123], 0
	v_mov_b64_e32 v[124:125], 0
	v_mov_b64_e32 v[126:127], 0
	s_branch .LBB0_1908

;     ...
;         const bool has_next = S.next(ui + 1, nxt);
;         const char* nA = has_next ? (const char*)g.A + (size_t)nxt.pm * tA : cA; const char* nB = has_next ? (const char*)g.Bt + (size_t)nxt.pn * tB : cB;
;     ...
; #pragma unroll
;         for (int a = 0; a < 2; ++a)
; #pragma unroll
;             for (int b = 0; b < 2; ++b)
; #pragma unroll
;                 for (int m = 0; m < 4; ++m)
; #pragma unroll
;                     for (int n = 0; n < 2; ++n) acc[a][b][m][n] = (f32x4){0.f, 0.f, 0.f, 0.f};
;         cur = nxt; cA = nA; cB = nB; ++ui;
.LBB0_1977:
	s_ashr_i32 s43, s42, 31
	s_lshl_b64 s[56:57], s[42:43], 19
	s_add_u32 s56, s88, s56
	s_addc_u32 s57, s89, s57
	s_and_b64 s[58:59], s[52:53], exec
	v_mov_b64_e32 v[0:1], 0
	s_cselect_b32 s43, s57, s37
	s_cselect_b32 s93, s56, s36
	s_mov_b32 s78, 0
	s_mov_b64 s[62:63], -1
	s_mov_b64 s[58:59], 0
	v_mov_b64_e32 v[2:3], 0
	v_mov_b64_e32 v[4:5], 0
	v_mov_b64_e32 v[6:7], 0
	v_mov_b64_e32 v[8:9], 0
	v_mov_b64_e32 v[10:11], 0
	v_mov_b64_e32 v[12:13], 0
	v_mov_b64_e32 v[14:15], 0
	v_mov_b64_e32 v[16:17], 0
	v_mov_b64_e32 v[18:19], 0
	v_mov_b64_e32 v[20:21], 0
	v_mov_b64_e32 v[22:23], 0
	v_mov_b64_e32 v[24:25], 0
	v_mov_b64_e32 v[26:27], 0
	v_mov_b64_e32 v[28:29], 0
	v_mov_b64_e32 v[30:31], 0
	v_mov_b64_e32 v[32:33], 0
	v_mov_b64_e32 v[34:35], 0
	v_mov_b64_e32 v[36:37], 0
	v_mov_b64_e32 v[38:39], 0
	v_mov_b64_e32 v[40:41], 0
	v_mov_b64_e32 v[42:43], 0
	v_mov_b64_e32 v[44:45], 0
	v_mov_b64_e32 v[46:47], 0
	v_mov_b64_e32 v[48:49], 0
	v_mov_b64_e32 v[50:51], 0
	v_mov_b64_e32 v[52:53], 0
	v_mov_b64_e32 v[54:55], 0
	v_mov_b64_e32 v[56:57], 0
	v_mov_b64_e32 v[58:59], 0
	v_mov_b64_e32 v[60:61], 0
	v_mov_b64_e32 v[62:63], 0
	v_mov_b64_e32 v[64:65], 0
	v_mov_b64_e32 v[66:67], 0
	v_mov_b64_e32 v[68:69], 0
	v_mov_b64_e32 v[70:71], 0
	v_mov_b64_e32 v[72:73], 0
	v_mov_b64_e32 v[74:75], 0
	v_mov_b64_e32 v[76:77], 0
	v_mov_b64_e32 v[78:79], 0
	v_mov_b64_e32 v[80:81], 0
	v_mov_b64_e32 v[82:83], 0
	v_mov_b64_e32 v[84:85], 0
	v_mov_b64_e32 v[86:87], 0
	v_mov_b64_e32 v[88:89], 0
	v_mov_b64_e32 v[90:91], 0
	v_mov_b64_e32 v[92:93], 0
	v_mov_b64_e32 v[94:95], 0
	v_mov_b64_e32 v[96:97], 0
	v_mov_b64_e32 v[98:99], 0
	v_mov_b64_e32 v[100:101], 0
	v_mov_b64_e32 v[102:103], 0
	v_mov_b64_e32 v[104:105], 0
	v_mov_b64_e32 v[106:107], 0
	v_mov_b64_e32 v[108:109], 0
	v_mov_b64_e32 v[110:111], 0
	v_mov_b64_e32 v[112:113], 0
	v_mov_b64_e32 v[114:115], 0
	v_mov_b64_e32 v[116:117], 0
	v_mov_b64_e32 v[118:119], 0
	v_mov_b64_e32 v[120:121], 0
	v_mov_b64_e32 v[122:123], 0
	v_mov_b64_e32 v[124:125], 0
	v_mov_b64_e32 v[126:127], 0
	s_branch .LBB0_1981

;     ...
;         const bool has_next = S.next(ui + 1, nxt);
;         const char* nA = has_next ? (const char*)g.A + (size_t)nxt.pm * tA : cA; const char* nB = has_next ? (const char*)g.Bt + (size_t)nxt.pn * tB : cB;
;     ...
; #pragma unroll
;         for (int a = 0; a < 2; ++a)
; #pragma unroll
;             for (int b = 0; b < 2; ++b)
; #pragma unroll
;                 for (int m = 0; m < 4; ++m)
; #pragma unroll
;                     for (int n = 0; n < 2; ++n) acc[a][b][m][n] = (f32x4){0.f, 0.f, 0.f, 0.f};
;         cur = nxt; cA = nA; cB = nB; ++ui;
.LBB0_2098:
	s_ashr_i32 s25, s24, 31
	v_cmp_lt_i64_e32 vcc, s[28:29], v[140:141]
	s_lshl_b64 s[28:29], s[24:25], 19
	s_add_u32 s30, s10, s28
	s_addc_u32 s31, s11, s29
	s_and_b64 s[28:29], vcc, exec
	s_cselect_b32 s25, s31, s37
	s_cselect_b32 s44, s30, s36
	s_ashr_i32 s35, s34, 31
	s_lshl_b64 s[28:29], s[34:35], 19
	s_add_u32 s28, s20, s28
	s_addc_u32 s29, s21, s29
	s_and_b64 s[40:41], vcc, exec
	s_cselect_b32 s35, s29, s39
	s_cselect_b32 s45, s28, s38
	s_add_u32 s69, s38, 0x100
	s_addc_u32 s70, s39, 0
	s_add_u32 s36, s36, 0x40080
	v_mov_b64_e32 v[0:1], 0
	s_addc_u32 s37, s37, 0
	s_mov_b32 s71, -2
	v_mov_b64_e32 v[2:3], 0
	v_mov_b64_e32 v[4:5], 0
	v_mov_b64_e32 v[6:7], 0
	v_mov_b64_e32 v[8:9], 0
	v_mov_b64_e32 v[10:11], 0
	v_mov_b64_e32 v[12:13], 0
	v_mov_b64_e32 v[14:15], 0
	v_mov_b64_e32 v[16:17], 0
	v_mov_b64_e32 v[18:19], 0
	v_mov_b64_e32 v[20:21], 0
	v_mov_b64_e32 v[22:23], 0
	v_mov_b64_e32 v[24:25], 0
	v_mov_b64_e32 v[26:27], 0
	v_mov_b64_e32 v[28:29], 0
	v_mov_b64_e32 v[30:31], 0
	v_mov_b64_e32 v[32:33], 0
	v_mov_b64_e32 v[34:35], 0
	v_mov_b64_e32 v[36:37], 0
	v_mov_b64_e32 v[38:39], 0
	v_mov_b64_e32 v[40:41], 0
	v_mov_b64_e32 v[42:43], 0
	v_mov_b64_e32 v[44:45], 0
	v_mov_b64_e32 v[46:47], 0
	v_mov_b64_e32 v[48:49], 0
	v_mov_b64_e32 v[50:51], 0
	v_mov_b64_e32 v[52:53], 0
	v_mov_b64_e32 v[54:55], 0
	v_mov_b64_e32 v[56:57], 0
	v_mov_b64_e32 v[58:59], 0
	v_mov_b64_e32 v[60:61], 0
	v_mov_b64_e32 v[62:63], 0
	v_mov_b64_e32 v[64:65], 0
	v_mov_b64_e32 v[66:67], 0
	v_mov_b64_e32 v[68:69], 0
	v_mov_b64_e32 v[70:71], 0
	v_mov_b64_e32 v[72:73], 0
	v_mov_b64_e32 v[74:75], 0
	v_mov_b64_e32 v[76:77], 0
	v_mov_b64_e32 v[78:79], 0
	v_mov_b64_e32 v[80:81], 0
	v_mov_b64_e32 v[82:83], 0
	v_mov_b64_e32 v[84:85], 0
	v_mov_b64_e32 v[86:87], 0
	v_mov_b64_e32 v[88:89], 0
	v_mov_b64_e32 v[90:91], 0
	v_mov_b64_e32 v[92:93], 0
	v_mov_b64_e32 v[94:95], 0
	v_mov_b64_e32 v[96:97], 0
	v_mov_b64_e32 v[98:99], 0
	v_mov_b64_e32 v[100:101], 0
	v_mov_b64_e32 v[102:103], 0
	v_mov_b64_e32 v[104:105], 0
	v_mov_b64_e32 v[106:107], 0
	v_mov_b64_e32 v[108:109], 0
	v_mov_b64_e32 v[110:111], 0
	v_mov_b64_e32 v[112:113], 0
	v_mov_b64_e32 v[114:115], 0
	v_mov_b64_e32 v[116:117], 0
	v_mov_b64_e32 v[118:119], 0
	v_mov_b64_e32 v[120:121], 0
	v_mov_b64_e32 v[122:123], 0
	v_mov_b64_e32 v[124:125], 0
	v_mov_b64_e32 v[126:127], 0

;     ...
;         const bool has_next = S.next(ui + 1, nxt);
;         const char* nA = has_next ? (const char*)g.A + (size_t)nxt.pm * tA : cA; const char* nB = has_next ? (const char*)g.Bt + (size_t)nxt.pn * tB : cB;
;     ...
; #pragma unroll
;         for (int a = 0; a < 2; ++a)
; #pragma unroll
;             for (int b = 0; b < 2; ++b)
; #pragma unroll
;                 for (int m = 0; m < 4; ++m)
; #pragma unroll
;                     for (int n = 0; n < 2; ++n) acc[a][b][m][n] = (f32x4){0.f, 0.f, 0.f, 0.f};
;         cur = nxt; cA = nA; cB = nB; ++ui;
.LBB0_2121:
	s_ashr_i32 s21, s20, 31
	v_cmp_lt_i64_e64 s[38:39], s[24:25], 64
	s_lshl_b64 s[24:25], s[20:21], 19
	s_add_u32 s26, s42, s24
	s_addc_u32 s27, s43, s25
	s_and_b64 s[24:25], s[38:39], exec
	s_cselect_b32 s21, s27, s35
	s_cselect_b32 s44, s26, s34
	s_ashr_i32 s29, s28, 31
	s_lshl_b64 s[24:25], s[28:29], 19
	s_add_u32 s24, s12, s24
	s_addc_u32 s25, s13, s25
	s_and_b64 s[38:39], s[38:39], exec
	s_cselect_b32 s29, s25, s37
	s_cselect_b32 s45, s24, s36
	s_add_u32 s69, s36, 0x100
	s_addc_u32 s70, s37, 0
	s_add_u32 s34, s34, 0x40080
	v_mov_b64_e32 v[0:1], 0
	s_addc_u32 s35, s35, 0
	s_mov_b32 s71, -2
	v_mov_b64_e32 v[2:3], 0
	v_mov_b64_e32 v[4:5], 0
	v_mov_b64_e32 v[6:7], 0
	v_mov_b64_e32 v[8:9], 0
	v_mov_b64_e32 v[10:11], 0
	v_mov_b64_e32 v[12:13], 0
	v_mov_b64_e32 v[14:15], 0
	v_mov_b64_e32 v[16:17], 0
	v_mov_b64_e32 v[18:19], 0
	v_mov_b64_e32 v[20:21], 0
	v_mov_b64_e32 v[22:23], 0
	v_mov_b64_e32 v[24:25], 0
	v_mov_b64_e32 v[26:27], 0
	v_mov_b64_e32 v[28:29], 0
	v_mov_b64_e32 v[30:31], 0
	v_mov_b64_e32 v[32:33], 0
	v_mov_b64_e32 v[34:35], 0
	v_mov_b64_e32 v[36:37], 0
	v_mov_b64_e32 v[38:39], 0
	v_mov_b64_e32 v[40:41], 0
	v_mov_b64_e32 v[42:43], 0
	v_mov_b64_e32 v[44:45], 0
	v_mov_b64_e32 v[46:47], 0
	v_mov_b64_e32 v[48:49], 0
	v_mov_b64_e32 v[50:51], 0
	v_mov_b64_e32 v[52:53], 0
	v_mov_b64_e32 v[54:55], 0
	v_mov_b64_e32 v[56:57], 0
	v_mov_b64_e32 v[58:59], 0
	v_mov_b64_e32 v[60:61], 0
	v_mov_b64_e32 v[62:63], 0
	v_mov_b64_e32 v[64:65], 0
	v_mov_b64_e32 v[66:67], 0
	v_mov_b64_e32 v[68:69], 0
	v_mov_b64_e32 v[70:71], 0
	v_mov_b64_e32 v[72:73], 0
	v_mov_b64_e32 v[74:75], 0
	v_mov_b64_e32 v[76:77], 0
	v_mov_b64_e32 v[78:79], 0
	v_mov_b64_e32 v[80:81], 0
	v_mov_b64_e32 v[82:83], 0
	v_mov_b64_e32 v[84:85], 0
	v_mov_b64_e32 v[86:87], 0
	v_mov_b64_e32 v[88:89], 0
	v_mov_b64_e32 v[90:91], 0
	v_mov_b64_e32 v[92:93], 0
	v_mov_b64_e32 v[94:95], 0
	v_mov_b64_e32 v[96:97], 0
	v_mov_b64_e32 v[98:99], 0
	v_mov_b64_e32 v[100:101], 0
	v_mov_b64_e32 v[102:103], 0
	v_mov_b64_e32 v[104:105], 0
	v_mov_b64_e32 v[106:107], 0
	v_mov_b64_e32 v[108:109], 0
	v_mov_b64_e32 v[110:111], 0
	v_mov_b64_e32 v[112:113], 0
	v_mov_b64_e32 v[114:115], 0
	v_mov_b64_e32 v[116:117], 0
	v_mov_b64_e32 v[118:119], 0
	v_mov_b64_e32 v[120:121], 0
	v_mov_b64_e32 v[122:123], 0
	v_mov_b64_e32 v[124:125], 0
	v_mov_b64_e32 v[126:127], 0

;     ...
;         const bool has_next = S.next(ui + 1, nxt);
;         const char* nA = has_next ? (const char*)g.A + (size_t)nxt.pm * tA : cA; const char* nB = has_next ? (const char*)g.Bt + (size_t)nxt.pn * tB : cB;
;     ...
; #pragma unroll
;         for (int a = 0; a < 2; ++a)
; #pragma unroll
;             for (int b = 0; b < 2; ++b)
; #pragma unroll
;                 for (int m = 0; m < 4; ++m)
; #pragma unroll
;                     for (int n = 0; n < 2; ++n) acc[a][b][m][n] = (f32x4){0.f, 0.f, 0.f, 0.f};
;         cur = nxt; cA = nA; cB = nB; ++ui;
.LBB0_2160:
	s_ashr_i32 s35, s34, 31
	s_lshl_b64 s[36:37], s[34:35], 21
	s_add_u32 s36, s14, s36
	s_addc_u32 s37, s15, s37
	s_and_b64 s[38:39], s[12:13], exec
	s_cselect_b32 s33, s37, s53
	s_cselect_b32 s35, s36, s52
	s_ashr_i32 s31, s30, 31
	s_lshl_b64 s[38:39], s[30:31], 21
	s_add_u32 s38, s20, s38
	s_addc_u32 s39, s21, s39
	s_and_b64 s[44:45], s[12:13], exec
	s_cselect_b32 s31, s39, s55
	s_cselect_b32 s41, s38, s54
	s_add_u32 s43, s52, 0x100000
	s_addc_u32 s44, s53, 0
	s_lshl_b32 s56, s34, 6
	s_ashr_i32 s57, s56, 31
	s_lshl_b64 s[56:57], s[56:57], 2
	s_add_u32 s56, s66, s56
	v_mov_b64_e32 v[0:1], 0
	s_addc_u32 s57, s67, s57
	s_mov_b32 s45, 0
	s_waitcnt lgkmcnt(0)
	v_mov_b64_e32 v[2:3], 0
	v_mov_b64_e32 v[4:5], 0
	v_mov_b64_e32 v[6:7], 0
	v_mov_b64_e32 v[8:9], 0
	v_mov_b64_e32 v[10:11], 0
	v_mov_b64_e32 v[12:13], 0
	v_mov_b64_e32 v[14:15], 0
	v_mov_b64_e32 v[16:17], 0
	v_mov_b64_e32 v[18:19], 0
	v_mov_b64_e32 v[20:21], 0
	v_mov_b64_e32 v[22:23], 0
	v_mov_b64_e32 v[24:25], 0
	v_mov_b64_e32 v[26:27], 0
	v_mov_b64_e32 v[28:29], 0
	v_mov_b64_e32 v[30:31], 0
	v_mov_b64_e32 v[32:33], 0
	v_mov_b64_e32 v[34:35], 0
	v_mov_b64_e32 v[36:37], 0
	v_mov_b64_e32 v[38:39], 0
	v_mov_b64_e32 v[40:41], 0
	v_mov_b64_e32 v[42:43], 0
	v_mov_b64_e32 v[44:45], 0
	v_mov_b64_e32 v[46:47], 0
	v_mov_b64_e32 v[48:49], 0
	v_mov_b64_e32 v[50:51], 0
	v_mov_b64_e32 v[52:53], 0
	v_mov_b64_e32 v[54:55], 0
	v_mov_b64_e32 v[56:57], 0
	v_mov_b64_e32 v[58:59], 0
	v_mov_b64_e32 v[60:61], 0
	v_mov_b64_e32 v[62:63], 0
	v_mov_b64_e32 v[64:65], 0
	v_mov_b64_e32 v[66:67], 0
	v_mov_b64_e32 v[68:69], 0
	v_mov_b64_e32 v[70:71], 0
	v_mov_b64_e32 v[72:73], 0
	v_mov_b64_e32 v[74:75], 0
	v_mov_b64_e32 v[76:77], 0
	v_mov_b64_e32 v[78:79], 0
	v_mov_b64_e32 v[80:81], 0
	v_mov_b64_e32 v[82:83], 0
	v_mov_b64_e32 v[84:85], 0
	v_mov_b64_e32 v[86:87], 0
	v_mov_b64_e32 v[88:89], 0
	v_mov_b64_e32 v[90:91], 0
	v_mov_b64_e32 v[92:93], 0
	v_mov_b64_e32 v[94:95], 0
	v_mov_b64_e32 v[96:97], 0
	v_mov_b64_e32 v[98:99], 0
	v_mov_b64_e32 v[100:101], 0
	v_mov_b64_e32 v[102:103], 0
	v_mov_b64_e32 v[104:105], 0
	v_mov_b64_e32 v[106:107], 0
	v_mov_b64_e32 v[108:109], 0
	v_mov_b64_e32 v[110:111], 0
	v_mov_b64_e32 v[112:113], 0
	v_mov_b64_e32 v[114:115], 0
	v_mov_b64_e32 v[116:117], 0
	v_mov_b64_e32 v[118:119], 0
	v_mov_b64_e32 v[120:121], 0
	v_mov_b64_e32 v[122:123], 0
	v_mov_b64_e32 v[124:125], 0
	v_mov_b64_e32 v[126:127], 0
	s_branch .LBB0_2164

;     ...
;         const bool has_next = S.next(ui + 1, nxt);
;         const char* nA = has_next ? (const char*)g.A + (size_t)nxt.pm * tA : cA; const char* nB = has_next ? (const char*)g.Bt + (size_t)nxt.pn * tB : cB;
; #pragma unroll 1
;         for (int t = 0; t < nt; t += 2) {
;             const bool last = (t == nt - 2);
;             const char* a1 = cA + (size_t)(t + 1) * kstep;
;             const char* a2 = last ? nA : cA + (size_t)(t + 2) * kstep; const char* b2 = last ? nB : cB + (size_t)(t + 2) * kstep;
;             const char* a3 = a2 + kstep; const char* b3 = b2 + kstep;
;             if (last && has_next) PG8_A_READY(nxt);
;     ...
; #pragma unroll
;         for (int a = 0; a < 2; ++a)
; #pragma unroll
;             for (int b = 0; b < 2; ++b)
; #pragma unroll
;                 for (int m = 0; m < 4; ++m)
; #pragma unroll
;                     for (int n = 0; n < 2; ++n) acc[a][b][m][n] = (f32x4){0.f, 0.f, 0.f, 0.f};
;         cur = nxt; cA = nA; cB = nB; ++ui;
.LBB0_2229:
	s_ashr_i32 s43, s42, 31
	s_lshl_b64 s[54:55], s[42:43], 21
	s_add_u32 s54, s81, s54
	s_addc_u32 s55, s82, s55
	s_and_b64 s[56:57], s[52:53], exec
	s_cselect_b32 s43, s55, s31
	s_cselect_b32 s90, s54, s30
	s_ashr_i32 s41, s40, 31
	s_lshl_b64 s[56:57], s[40:41], 21
	s_add_u32 s56, s83, s56
	s_addc_u32 s57, s84, s57
	s_and_b64 s[58:59], s[52:53], exec
	s_cselect_b32 s41, s57, s35
	s_cselect_b32 s91, s56, s34
	s_add_u32 s92, s30, 0x100000
	s_addc_u32 s93, s31, 0
	s_lshl_b32 s58, s42, 6
	s_ashr_i32 s59, s58, 31
	s_lshl_b64 s[58:59], s[58:59], 2
	s_add_u32 s58, s68, s58
	v_mov_b64_e32 v[0:1], 0
	s_addc_u32 s59, s69, s59
	s_mov_b32 s94, 0
	v_mov_b64_e32 v[2:3], 0
	v_mov_b64_e32 v[4:5], 0
	v_mov_b64_e32 v[6:7], 0
	v_mov_b64_e32 v[8:9], 0
	v_mov_b64_e32 v[10:11], 0
	v_mov_b64_e32 v[12:13], 0
	v_mov_b64_e32 v[14:15], 0
	v_mov_b64_e32 v[16:17], 0
	v_mov_b64_e32 v[18:19], 0
	v_mov_b64_e32 v[20:21], 0
	v_mov_b64_e32 v[22:23], 0
	v_mov_b64_e32 v[24:25], 0
	v_mov_b64_e32 v[26:27], 0
	v_mov_b64_e32 v[28:29], 0
	v_mov_b64_e32 v[30:31], 0
	v_mov_b64_e32 v[32:33], 0
	v_mov_b64_e32 v[34:35], 0
	v_mov_b64_e32 v[36:37], 0
	v_mov_b64_e32 v[38:39], 0
	v_mov_b64_e32 v[40:41], 0
	v_mov_b64_e32 v[42:43], 0
	v_mov_b64_e32 v[44:45], 0
	v_mov_b64_e32 v[46:47], 0
	v_mov_b64_e32 v[48:49], 0
	v_mov_b64_e32 v[50:51], 0
	v_mov_b64_e32 v[52:53], 0
	v_mov_b64_e32 v[54:55], 0
	v_mov_b64_e32 v[56:57], 0
	v_mov_b64_e32 v[58:59], 0
	v_mov_b64_e32 v[60:61], 0
	v_mov_b64_e32 v[62:63], 0
	v_mov_b64_e32 v[64:65], 0
	v_mov_b64_e32 v[66:67], 0
	v_mov_b64_e32 v[68:69], 0
	v_mov_b64_e32 v[70:71], 0
	v_mov_b64_e32 v[72:73], 0
	v_mov_b64_e32 v[74:75], 0
	v_mov_b64_e32 v[76:77], 0
	v_mov_b64_e32 v[78:79], 0
	v_mov_b64_e32 v[80:81], 0
	v_mov_b64_e32 v[82:83], 0
	v_mov_b64_e32 v[84:85], 0
	v_mov_b64_e32 v[86:87], 0
	v_mov_b64_e32 v[88:89], 0
	v_mov_b64_e32 v[90:91], 0
	v_mov_b64_e32 v[92:93], 0
	v_mov_b64_e32 v[94:95], 0
	v_mov_b64_e32 v[96:97], 0
	v_mov_b64_e32 v[98:99], 0
	v_mov_b64_e32 v[100:101], 0
	v_mov_b64_e32 v[102:103], 0
	v_mov_b64_e32 v[104:105], 0
	v_mov_b64_e32 v[106:107], 0
	v_mov_b64_e32 v[108:109], 0
	v_mov_b64_e32 v[110:111], 0
	v_mov_b64_e32 v[112:113], 0
	v_mov_b64_e32 v[114:115], 0
	v_mov_b64_e32 v[116:117], 0
	v_mov_b64_e32 v[118:119], 0
	v_mov_b64_e32 v[120:121], 0
	v_mov_b64_e32 v[122:123], 0
	v_mov_b64_e32 v[124:125], 0
	v_mov_b64_e32 v[126:127], 0
	s_branch .LBB0_2233
